# P5: A2 hand-scheduled + raw r/k/v prefetch packing deferred to next head (no wait after issue) + per-channel parameter loads hoisted to loop top
# speedup vs baseline: 1.1186x; 1.0040x over previous
; #define LAS __attribute__((address_space(3)))
; __device__ __forceinline__ void st4_lds(LAS unsigned char* p, f32x4 v) { v2u w; w.x = pk2(v[0], v[1]); w.y = pk2(v[2], v[3]); *(LAS v2u*)p = w; }
; __device__ __forceinline__ void rwkv_chunk_group(Frame& F, int bc, unsigned long long& tsub) {
;     ...
;     bf16x8 xw[2], xa[2], xg[5];
;     { const int m0 = 16 * (w >> 1);
; #pragma unroll
;       for (int k = 0; k < 2; ++k) { xw[k] = *(const LAS bf16x8*)(L + L_XW + (m0 + fr) * LD + fq * 16 + k * 64); xa[k] = *(const LAS bf16x8*)(L + L_XA + (m0 + fr) * LD + fq * 16 + k * 64); }
; #pragma unroll
;       for (int k = 0; k < 5; ++k) xg[k] = *(const LAS bf16x8*)(L + L_XG + (m0 + fr) * 336 + fq * 16 + k * 64); }
;     const int ch = lane, tb = 8 * w;
;     bf16 raw[9][3];
;     { const bool has = (c * CH + tb > 0);
; #pragma unroll
;       for (int tt = 0; tt < 9; ++tt) { const size_t off = (size_t)(row0 + tb + tt - 1) * PRW + (F.vcu & (RW_H - 1)) * 64 + ch;
;           if (tt > 0 || has) { raw[tt][0] = P[off]; raw[tt][1] = P[off + 512]; raw[tt][2] = P[off + 1024]; } else { raw[tt][0] = 0; raw[tt][1] = 0; raw[tt][2] = 0; } } }
;     ...
;     for (int q = 0; q < 2; ++q) { const int tw = 2 * w + q, p0 = 16 * (tw >> 2), q0 = 16 * (tw & 3); const int o = (p0 + fr) * LD + (q0 + 4 * fq) * 2;
;         const f32x4 ap = mm_tile(L + L_TT, LD, q0, L + L_ATT, LD, p0, 2, Z4, fr, fq);
;         const f32x4 w1 = mm_tile(L + L_NAK, LD, q0, L + L_VT, LD, p0, 2, Z4, fr, fq);
;         st4_lds(L + L_APT + o, ap); st4_lds(L + L_W1T + o, w1); }
.LBB0_1407:
	s_waitcnt lgkmcnt(0)
	s_barrier
	ds_read_b128 v[0:3], v134
	ds_read_b128 v[4:7], v134 offset:64
	ds_read_b128 v[8:11], v135
	ds_read_b128 v[12:15], v135 offset:64
	ds_read_b128 v[16:19], v136
	ds_read_b128 v[20:23], v136 offset:64
	ds_read_b128 v[24:27], v136 offset:128
	ds_read_b128 v[28:31], v136 offset:192
	ds_read_b128 v[32:35], v136 offset:256
	v_readlane_b32 s14, v254, 22
	s_cmp_gt_i32 s70, s14
	s_cselect_b64 s[16:17], -1, 0
	v_readlane_b32 s14, v254, 24
	v_writelane_b32 v254, s16, 60
	s_add_i32 s64, s14, s13
	v_mov_b32_e32 v153, 0
	v_writelane_b32 v254, s17, 61
	s_and_b64 vcc, exec, s[16:17]
	v_mov_b32_e32 v202, 0
	v_mov_b32_e32 v215, 0
	s_cbranch_vccz .LBB0_1409
	s_ashr_i32 s65, s64, 31
	s_lshl_b64 s[14:15], s[64:65], 12
	v_lshl_add_u64 v[36:37], v[48:49], 0, s[14:15]
	global_load_ushort v153, v[36:37], off
	global_load_ushort v202, v[36:37], off offset:1024
	global_load_ushort v215, v[36:37], off offset:2048
.LBB0_1409:
	v_readlane_b32 s16, v254, 23
	s_add_i32 s14, s13, s16
	s_ashr_i32 s15, s14, 31
	s_lshl_b64 s[14:15], s[14:15], 12
	v_writelane_b32 v255, s14, 0
	s_nop 1
	v_writelane_b32 v255, s15, 1
	v_lshl_add_u64 v[36:37], v[48:49], 0, s[14:15]
	s_add_i32 s14, s64, 2
	s_ashr_i32 s15, s14, 31
	s_lshl_b64 s[14:15], s[14:15], 12
	v_writelane_b32 v255, s14, 2
	global_load_ushort v154, v[36:37], off
	global_load_ushort v203, v[36:37], off offset:1024
	global_load_ushort v216, v[36:37], off offset:2048
	v_writelane_b32 v255, s15, 3
	v_lshl_add_u64 v[36:37], v[48:49], 0, s[14:15]
	s_add_i32 s14, s64, 3
	s_ashr_i32 s15, s14, 31
	s_lshl_b64 s[14:15], s[14:15], 12
	v_writelane_b32 v255, s14, 4
	global_load_ushort v155, v[36:37], off
	global_load_ushort v204, v[36:37], off offset:1024
	global_load_ushort v217, v[36:37], off offset:2048
	v_writelane_b32 v255, s15, 5
	v_lshl_add_u64 v[36:37], v[48:49], 0, s[14:15]
	s_add_i32 s14, s64, 4
	s_ashr_i32 s15, s14, 31
	s_lshl_b64 s[14:15], s[14:15], 12
	v_writelane_b32 v255, s14, 6
	global_load_ushort v156, v[36:37], off
	global_load_ushort v205, v[36:37], off offset:1024
	global_load_ushort v218, v[36:37], off offset:2048
	v_writelane_b32 v255, s15, 7
	v_lshl_add_u64 v[36:37], v[48:49], 0, s[14:15]
	s_add_i32 s14, s64, 5
	s_ashr_i32 s15, s14, 31
	s_lshl_b64 s[14:15], s[14:15], 12
	v_writelane_b32 v255, s14, 8
	global_load_ushort v157, v[36:37], off
	global_load_ushort v206, v[36:37], off offset:1024
	global_load_ushort v219, v[36:37], off offset:2048
	v_writelane_b32 v255, s15, 9
	v_lshl_add_u64 v[36:37], v[48:49], 0, s[14:15]
	s_add_i32 s14, s64, 6
	s_ashr_i32 s15, s14, 31
	s_lshl_b64 s[14:15], s[14:15], 12
	v_writelane_b32 v255, s14, 10
	global_load_ushort v158, v[36:37], off
	global_load_ushort v207, v[36:37], off offset:1024
	global_load_ushort v220, v[36:37], off offset:2048
	v_writelane_b32 v255, s15, 11
	v_lshl_add_u64 v[36:37], v[48:49], 0, s[14:15]
	s_add_i32 s14, s64, 7
	s_ashr_i32 s15, s14, 31
	s_lshl_b64 s[14:15], s[14:15], 12
	v_writelane_b32 v255, s14, 12
	global_load_ushort v159, v[36:37], off
	global_load_ushort v212, v[36:37], off offset:1024
	global_load_ushort v221, v[36:37], off offset:2048
	v_writelane_b32 v255, s15, 13
	v_lshl_add_u64 v[36:37], v[48:49], 0, s[14:15]
	s_add_i32 s14, s64, 8
	s_ashr_i32 s15, s14, 31
	s_lshl_b64 s[14:15], s[14:15], 12
	global_load_ushort v162, v[36:37], off
	global_load_ushort v213, v[36:37], off offset:1024
	global_load_ushort v222, v[36:37], off offset:2048
	v_writelane_b32 v255, s14, 14
	s_nop 1
	v_lshl_add_u64 v[36:37], v[48:49], 0, s[14:15]
	global_load_ushort v163, v[36:37], off
	global_load_ushort v214, v[36:37], off offset:1024
	global_load_ushort v223, v[36:37], off offset:2048
	v_writelane_b32 v255, s15, 15
	v_readlane_b32 s14, v254, 27
	v_readlane_b32 s15, v254, 28
	s_waitcnt lgkmcnt(0)
	s_barrier
	s_andn2_b64 vcc, exec, s[14:15]
	v_readlane_b32 s14, v254, 57
	v_readlane_b32 s15, v254, 58
	s_mov_b32 s13, s14
	s_mov_b32 s14, s16
	s_mov_b32 s15, s93
	s_cbranch_vccz .LBB0_1471
.LBB0_1410:
	s_lshl_b32 s11, s11, 9
	s_ashr_i32 s65, s64, 31
	s_add_i32 s11, s11, s12
	s_lshl_b64 s[12:13], s[64:65], 12
	v_writelane_b32 v254, s12, 62
	s_mov_b32 s16, s93
	s_waitcnt vmcnt(0)
	v_writelane_b32 v254, s13, 63
	s_mov_b32 s12, 0
	s_branch .LBB0_1412
.LBB0_1411:
	v_add_u32_e32 v52, v108, v110
	ds_read_b128 v[36:39], v52
	ds_read_b128 v[40:43], v107 offset:36864
	v_add_u32_e32 v92, v109, v110
	ds_read_b128 v[44:47], v92
	ds_read_b128 v[80:83], v107 offset:36928
	ds_read_b128 v[84:87], v52 offset:64
	v_add_u32_e32 v173, v108, v128
	s_lshl_b64 s[64:65], s[72:73], 1
	s_waitcnt lgkmcnt(3)
	v_mfma_f32_16x16x32_bf16 v[36:39], v[36:39], v[40:43], 0
	ds_read_b128 v[40:43], v107 offset:46080
	ds_read_b128 v[88:91], v107 offset:46144
	ds_read_b128 v[92:95], v92 offset:64
	v_lshl_add_u64 v[174:175], v[66:67], 0, s[64:65]
	s_mov_b32 s77, s95
	s_waitcnt lgkmcnt(2)
	v_mfma_f32_16x16x32_bf16 v[40:43], v[44:47], v[40:43], 0
	v_lshl_add_u64 v[176:177], v[74:75], 0, s[64:65]
	s_mov_b32 s93, s95
	s_cmp_lg_u32 s12, 8
	v_mfma_f32_16x16x32_bf16 v[36:39], v[84:87], v[80:83], v[36:39]
	s_waitcnt lgkmcnt(0)
	v_mfma_f32_16x16x32_bf16 v[40:43], v[92:95], v[88:91], v[40:43]
	v_add_u32_e32 v88, v109, v128
	s_nop 2
	v_cvt_pk_bf16_f32 v36, v36, v37
	v_cvt_pk_bf16_f32 v37, v38, v39
	s_nop 1
	v_cvt_pk_bf16_f32 v38, v40, v41
	v_cvt_pk_bf16_f32 v39, v42, v43
	ds_write2st64_b64 v142, v[36:37], v[38:39] offset1:18
	ds_read_b128 v[36:39], v173
	ds_read_b128 v[40:43], v107 offset:36864
	ds_read_b128 v[44:47], v88
	ds_read_b128 v[80:83], v173 offset:64
	ds_read_b128 v[84:87], v107 offset:36928
	s_waitcnt lgkmcnt(3)
	v_mfma_f32_16x16x32_bf16 v[36:39], v[36:39], v[40:43], 0
	ds_read_b128 v[40:43], v107 offset:46080
	ds_read_b128 v[88:91], v88 offset:64
	ds_read_b128 v[92:95], v107 offset:46144
	s_waitcnt lgkmcnt(2)
	v_mfma_f32_16x16x32_bf16 v[40:43], v[44:47], v[40:43], 0
	v_mfma_f32_16x16x32_bf16 v[36:39], v[80:83], v[84:87], v[36:39]
	s_waitcnt lgkmcnt(0)
	v_mfma_f32_16x16x32_bf16 v[40:43], v[88:91], v[92:95], v[40:43]
	s_nop 5
	v_cvt_pk_bf16_f32 v36, v36, v37
	v_cvt_pk_bf16_f32 v37, v38, v39
	v_cvt_pk_bf16_f32 v38, v40, v41
	v_cvt_pk_bf16_f32 v39, v42, v43
	ds_write2st64_b64 v143, v[36:37], v[38:39] offset1:18
	s_waitcnt lgkmcnt(0)
	s_barrier
; #define LAS __attribute__((address_space(3)))
; __device__ __forceinline__ void st4_lds(LAS unsigned char* p, f32x4 v) { v2u w; w.x = pk2(v[0], v[1]); w.y = pk2(v[2], v[3]); *(LAS v2u*)p = w; }
; __device__ __forceinline__ void st4_g(bf16* p, f32x4 v) { v2u w; w.x = pk2(v[0], v[1]); w.y = pk2(v[2], v[3]); *(GAS v2u*)p = w; }
; __device__ __forceinline__ f32x4 ld4_lds(const LAS unsigned char* p) { const v2u w = *(const LAS v2u*)p; return (f32x4){bflo(w.x), bfhi(w.x), bflo(w.y), bfhi(w.y)}; }
; #define LBAR() asm volatile("s_waitcnt lgkmcnt(0)\n\ts_barrier" ::: "memory")
; __device__ __forceinline__ void rwkv_chunk_group(Frame& F, int bc, unsigned long long& tsub) {
;     ...
;         bf16* RPp = (bf16*)(F.ws + WS_RP) + (size_t)item * 4096; bf16* PTp = (bf16*)(F.ws + WS_PT) + (size_t)item * 4096;
; #pragma unroll
;         for (int q = 0; q < 2; ++q) { const int tw = 2 * w + q, p0 = 16 * (tw >> 2), q0 = 16 * (tw & 3); const int p = p0 + fr; const int o = p * LD + (q0 + 4 * fq) * 2;
;             const f32x4 u0 = mm_tile(L + L_TT, LD, q0, L + L_W1T, LD, p0, 2, Z4, fr, fq);
;             const f32x4 rp = mm_tile(L + L_APT, LD, q0, L + L_NRB, LD, p0, 2, ld4_lds(L + L_RT + o), fr, fq);
;             f32x4 pt = mm_tile(L + L_APT, LD, q0, L + L_BH, LD, p0, 2, Z4, fr, fq);
;             const float wc = *(const LAS float*)(L + L_WC + p * 4);
; #pragma unroll
;             for (int v = 0; v < 4; ++v) if (p == q0 + 4 * fq + v) pt[v] += wc;
;             st4_lds(L + L_U0T + o, u0);
;             st4_g(RPp + p * 64 + q0 + 4 * fq, rp); st4_g(PTp + ((p0 >> 4) * 2 + (q0 >> 5)) * 512 + fr * 32 + (q0 & 16) + 4 * fq, pt); }
;     }
;     LBAR();
;     {
;         bf16* Y0p = (bf16*)(F.ws + WS_Y0) + (size_t)item * 4096; bf16* QCp = (bf16*)(F.ws + WS_QC) + (size_t)item * 4096;
; #pragma unroll
;         for (int q = 0; q < 2; ++q) { const int tw = 2 * w + q, p0 = 16 * (tw >> 2), q0 = 16 * (tw & 3); const int p = p0 + fr;
;             f32x4 y0 = mm_tile(L + L_VT, LD, q0, L + L_NRK, LD, p0, 2, Z4, fr, fq);
;             y0 = mm_tile(L + L_U0T, LD, q0, L + L_NRB, LD, p0, 2, y0, fr, fq);
;             f32x4 qc = mm_tile(L + L_KH, LD, q0, L + L_VT, LD, p0, 2, Z4, fr, fq);
;             qc = mm_tile(L + L_BH, LD, q0, L + L_U0T, LD, p0, 2, qc, fr, fq);
;             st4_g(Y0p + p * 64 + q0 + 4 * fq, y0); st4_g(QCp + p * 64 + q0 + 4 * fq, qc); }
;     }
;     LBAR();
	ds_read_b128 v[36:39], v76
	ds_read_b128 v[40:43], v76 offset:64
	ds_read_b128 v[44:47], v107 offset:55296
	ds_read_b128 v[80:83], v52
	ds_read_b128 v[84:87], v52 offset:64
	ds_read_b64 v[102:103], v78 offset:27648
	ds_read_b128 v[88:91], v107 offset:55360
	s_waitcnt lgkmcnt(4)
	v_mfma_f32_16x16x32_bf16 v[44:47], v[36:39], v[44:47], 0
	ds_read_b128 v[92:95], v107 offset:9216
	ds_read_b128 v[96:99], v107 offset:9280
	ds_read_b32 v52, v145
	s_waitcnt lgkmcnt(4)
	v_lshlrev_b32_e32 v100, 16, v102
	v_and_b32_e32 v101, 0xffff0000, v102
	s_waitcnt lgkmcnt(3)
	v_mfma_f32_16x16x32_bf16 v[44:47], v[40:43], v[88:91], v[44:47]
	v_lshlrev_b32_e32 v102, 16, v103
	v_and_b32_e32 v103, 0xffff0000, v103
	s_waitcnt lgkmcnt(2)
	v_mfma_f32_16x16x32_bf16 v[80:83], v[80:83], v[92:95], 0
	ds_read_b128 v[88:91], v144
	ds_read_b128 v[92:95], v144 offset:64
	s_waitcnt lgkmcnt(2)
	s_nop 0
	v_add_f32_e32 v178, v52, v44
	v_cndmask_b32_e64 v44, v44, v178, s[18:19]
	s_waitcnt lgkmcnt(1)
	v_mfma_f32_16x16x32_bf16 v[36:39], v[36:39], v[88:91], v[100:103]
	v_mfma_f32_16x16x32_bf16 v[80:83], v[84:87], v[96:99], v[80:83]
	v_add_f32_e32 v84, v52, v45
	v_cndmask_b32_e64 v45, v45, v84, s[20:21]
	v_add_f32_e32 v84, v52, v46
	s_waitcnt lgkmcnt(0)
	v_mfma_f32_16x16x32_bf16 v[36:39], v[40:43], v[92:95], v[36:39]
	v_add_f32_e32 v52, v52, v47
	s_nop 1
	v_cvt_pk_bf16_f32 v40, v80, v81
	v_cvt_pk_bf16_f32 v41, v82, v83
	ds_write_b64 v78, v[40:41] offset:18432
	v_lshl_add_u64 v[40:41], v[174:175], 0, s[76:77]
	s_nop 0
	v_cvt_pk_bf16_f32 v36, v36, v37
	v_cvt_pk_bf16_f32 v37, v38, v39
	global_store_dwordx2 v[40:41], v[36:37], off
	ds_read_b128 v[36:39], v77
	v_cndmask_b32_e64 v46, v46, v84, s[22:23]
	v_cndmask_b32_e64 v47, v47, v52, s[24:25]
	v_cvt_pk_bf16_f32 v40, v44, v45
	v_cvt_pk_bf16_f32 v41, v46, v47
	global_store_dwordx2 v[176:177], v[40:41], off
	ds_read_b128 v[40:43], v77 offset:64
	ds_read_b128 v[44:47], v107 offset:55296
	ds_read_b128 v[80:83], v173
	ds_read_b128 v[84:87], v173 offset:64
	ds_read_b64 v[102:103], v79 offset:27648
	ds_read_b128 v[88:91], v107 offset:55360
	s_waitcnt lgkmcnt(4)
	v_mfma_f32_16x16x32_bf16 v[44:47], v[36:39], v[44:47], 0
	ds_read_b128 v[92:95], v107 offset:9216
	ds_read_b128 v[96:99], v107 offset:9280
	ds_read_b32 v52, v145
	s_waitcnt lgkmcnt(4)
	v_lshlrev_b32_e32 v100, 16, v102
	v_and_b32_e32 v101, 0xffff0000, v102
	s_waitcnt lgkmcnt(3)
	v_mfma_f32_16x16x32_bf16 v[44:47], v[40:43], v[88:91], v[44:47]
	v_lshlrev_b32_e32 v102, 16, v103
	v_and_b32_e32 v103, 0xffff0000, v103
	s_waitcnt lgkmcnt(2)
	v_mfma_f32_16x16x32_bf16 v[80:83], v[80:83], v[92:95], 0
	ds_read_b128 v[88:91], v144
	ds_read_b128 v[92:95], v144 offset:64
	s_waitcnt lgkmcnt(2)
	s_nop 0
	v_add_f32_e32 v78, v52, v44
	v_cndmask_b32_e64 v44, v44, v78, s[26:27]
	s_waitcnt lgkmcnt(1)
	v_mfma_f32_16x16x32_bf16 v[36:39], v[36:39], v[88:91], v[100:103]
	v_add_f32_e32 v78, v52, v45
	v_cndmask_b32_e64 v45, v45, v78, s[28:29]
	v_add_f32_e32 v78, v52, v46
	v_mfma_f32_16x16x32_bf16 v[80:83], v[84:87], v[96:99], v[80:83]
	v_add_f32_e32 v52, v52, v47
	v_cndmask_b32_e64 v46, v46, v78, s[30:31]
	v_cndmask_b32_e64 v47, v47, v52, s[34:35]
	s_waitcnt lgkmcnt(0)
	v_mfma_f32_16x16x32_bf16 v[36:39], v[40:43], v[92:95], v[36:39]
	v_lshl_add_u64 v[102:103], v[68:69], 0, s[64:65]
	s_nop 1
	v_cvt_pk_bf16_f32 v40, v80, v81
	v_cvt_pk_bf16_f32 v41, v82, v83
	ds_write_b64 v79, v[40:41] offset:18432
	v_lshl_add_u64 v[40:41], v[174:175], 0, s[92:93]
	s_nop 0
	v_cvt_pk_bf16_f32 v36, v36, v37
	v_cvt_pk_bf16_f32 v37, v38, v39
	global_store_dwordx2 v[40:41], v[36:37], off
	v_cvt_pk_bf16_f32 v36, v44, v45
	v_cvt_pk_bf16_f32 v37, v46, v47
	global_store_dwordx2 v[176:177], v[36:37], off offset:32
	s_waitcnt lgkmcnt(0)
	s_barrier
	ds_read_b128 v[36:39], v76 offset:46080
	ds_read_b128 v[40:43], v146
	ds_read_b128 v[44:47], v76 offset:46144
	ds_read_b128 v[78:81], v146 offset:64
	s_waitcnt lgkmcnt(2)
	v_mfma_f32_16x16x32_bf16 v[36:39], v[36:39], v[40:43], 0
	ds_read_b128 v[82:85], v76 offset:18432
	ds_read_b128 v[86:89], v144
	s_waitcnt lgkmcnt(2)
	v_mfma_f32_16x16x32_bf16 v[36:39], v[44:47], v[78:81], v[36:39]
	ds_read_b128 v[44:47], v76 offset:18496
	ds_read_b128 v[90:93], v144 offset:64
	s_waitcnt lgkmcnt(2)
	v_mfma_f32_16x16x32_bf16 v[36:39], v[82:85], v[86:89], v[36:39]
	ds_read_b128 v[82:85], v76 offset:64512
	ds_read_b128 v[94:97], v107 offset:46080
	s_waitcnt lgkmcnt(2)
	v_mfma_f32_16x16x32_bf16 v[36:39], v[44:47], v[90:93], v[36:39]
	ds_read_b128 v[44:47], v76 offset:64576
	ds_read_b128 v[98:101], v107 offset:46144
	ds_read_b128 v[174:177], v76 offset:55296
	ds_read_b128 v[178:181], v107 offset:18432
	s_waitcnt lgkmcnt(4)
	v_mfma_f32_16x16x32_bf16 v[82:85], v[82:85], v[94:97], 0
	s_nop 1
	v_cvt_pk_bf16_f32 v36, v36, v37
	v_cvt_pk_bf16_f32 v37, v38, v39
	s_waitcnt lgkmcnt(2)
	v_mfma_f32_16x16x32_bf16 v[44:47], v[44:47], v[98:101], v[82:85]
	s_nop 2
	ds_read_b128 v[82:85], v76 offset:55360
	ds_read_b128 v[182:185], v107 offset:18496
	s_waitcnt lgkmcnt(2)
	v_mfma_f32_16x16x32_bf16 v[44:47], v[174:177], v[178:181], v[44:47]
	ds_read_b128 v[174:177], v77 offset:46080
	s_waitcnt lgkmcnt(1)
	v_mfma_f32_16x16x32_bf16 v[44:47], v[82:85], v[182:185], v[44:47]
	ds_read_b128 v[82:85], v77 offset:46144
	s_waitcnt lgkmcnt(1)
	v_mfma_f32_16x16x32_bf16 v[40:43], v[174:177], v[40:43], 0
	ds_read_b128 v[174:177], v77 offset:18432
	s_nop 3
	v_cvt_pk_bf16_f32 v44, v44, v45
	v_cvt_pk_bf16_f32 v45, v46, v47
	s_waitcnt lgkmcnt(1)
	v_mfma_f32_16x16x32_bf16 v[40:43], v[82:85], v[78:81], v[40:43]
	ds_read_b128 v[78:81], v77 offset:18496
	s_waitcnt lgkmcnt(1)
	v_mfma_f32_16x16x32_bf16 v[40:43], v[174:177], v[86:89], v[40:43]
	ds_read_b128 v[82:85], v77 offset:64512
	ds_read_b128 v[86:89], v77 offset:64576
	v_lshl_add_u64 v[174:175], v[70:71], 0, s[64:65]
	s_waitcnt lgkmcnt(2)
	v_mfma_f32_16x16x32_bf16 v[40:43], v[78:81], v[90:93], v[40:43]
	ds_read_b128 v[78:81], v77 offset:55296
	ds_read_b128 v[90:93], v77 offset:55360
	v_lshl_add_u64 v[76:77], v[174:175], 0, s[76:77]
	s_waitcnt lgkmcnt(3)
	v_mfma_f32_16x16x32_bf16 v[82:85], v[82:85], v[94:97], 0
	v_lshl_add_u64 v[94:95], v[102:103], 0, s[76:77]
	global_store_dwordx2 v[94:95], v[36:37], off
	global_store_dwordx2 v[76:77], v[44:45], off
	s_waitcnt lgkmcnt(2)
	v_mfma_f32_16x16x32_bf16 v[82:85], v[86:89], v[98:101], v[82:85]
	v_lshl_add_u64 v[44:45], v[102:103], 0, s[92:93]
	v_cvt_pk_bf16_f32 v40, v40, v41
	v_cvt_pk_bf16_f32 v41, v42, v43
	s_waitcnt lgkmcnt(1)
	v_mfma_f32_16x16x32_bf16 v[36:39], v[78:81], v[178:181], v[82:85]
	global_store_dwordx2 v[44:45], v[40:41], off
	v_lshl_add_u64 v[40:41], v[174:175], 0, s[92:93]
	s_waitcnt lgkmcnt(0)
	v_mfma_f32_16x16x32_bf16 v[36:39], v[90:93], v[182:185], v[36:39]
	s_nop 7
	v_cvt_pk_bf16_f32 v36, v36, v37
	v_cvt_pk_bf16_f32 v37, v38, v39
	global_store_dwordx2 v[40:41], v[36:37], off
	s_waitcnt lgkmcnt(0)
	s_barrier
	s_cbranch_scc0 .LBB0_1392
; #define LAS __attribute__((address_space(3)))
; #define LBAR() asm volatile("s_waitcnt lgkmcnt(0)\n\ts_barrier" ::: "memory")
; #define TSUB(k) do { } while (0)
; __device__ __forceinline__ void rwkv_chunk_group(Frame& F, int bc, unsigned long long& tsub) {
;     ...
;         asm volatile("s_waitcnt vmcnt(0)" ::: "memory"); LBAR();
;         f32x4 aw[2], aa[2], ag[2];
; #pragma unroll
;         for (int q = 0; q < 2; ++q) { const int n0 = 16 * ((2 * w + q) & 3); aw[q] = Z4; aa[q] = Z4; ag[q] = Z4;
;             const LAS unsigned char* wp = L + L_LWA + (n0 + fr) * 128 + fq * 16; const LAS unsigned char* gp = L + L_LG + (n0 + fr) * 64 + fq * 16;
; #pragma unroll
;             for (int k = 0; k < 2; ++k) { aw[q] = __builtin_amdgcn_mfma_f32_16x16x32_bf16(xw[k], *(const LAS bf16x8*)(wp + k * 64), aw[q], 0, 0, 0); aa[q] = __builtin_amdgcn_mfma_f32_16x16x32_bf16(xa[k], *(const LAS bf16x8*)(wp + 8192 + k * 64), aa[q], 0, 0, 0); }
; #pragma unroll
;             for (int k = 0; k < 5; ++k) ag[q] = __builtin_amdgcn_mfma_f32_16x16x32_bf16(xg[k], *(const LAS bf16x8*)(gp + k * 4096), ag[q], 0, 0, 0);
;         }
;         LBAR();
; #pragma unroll
;         for (int q = 0; q < 2; ++q) { const int tw = 2 * w + q, m0 = 16 * (tw >> 2), n0 = 16 * (tw & 3);
; #pragma unroll
;             for (int v = 0; v < 4; ++v) { const int t = m0 + 4 * fq + v, cc = n0 + fr;
;                 *(LAS float*)(L + L_WL + (t * 65 + cc) * 4) = aw[q][v]; *(LAS float*)(L + L_AL + (t * 65 + cc) * 4) = aa[q][v]; *(LAS float*)(L + L_GL + (t * 65 + cc) * 4) = ag[q][v]; } }
;         LBAR();
;     }
;     TSUB(1);
;     {
;         const int gc = h * 64 + ch;
;         const float mur = mu[gc], muk = mu[512 + gc], muv = mu[1024 + gc];
;         const float w0 = (PRM + 2048)[gc], a0 = (PRM + 2560)[gc], k_k = (PRM + 3072)[gc], k_a = (PRM + 3584)[gc], r_k = (PRM + 4096)[gc];
.LBB0_1412:
	s_waitcnt vmcnt(0)
	v_perm_b32 v160, v203, v202, s5
	v_perm_b32 v161, v216, v215, s5
	v_perm_b32 v166, v204, v203, s5
	v_perm_b32 v167, v217, v216, s5
	v_perm_b32 v168, v206, v205, s5
	v_perm_b32 v169, v219, v218, s5
	v_perm_b32 v170, v212, v207, s5
	v_perm_b32 v171, v221, v220, s5
	v_perm_b32 v165, v214, v213, s5
	v_perm_b32 v172, v223, v222, s5
	v_readlane_b32 s98, v254, 2
	v_readlane_b32 s100, v254, 20
	v_readlane_b32 s101, v254, 21
	s_add_i32 s98, s98, s12
	s_lshl_b32 s98, s98, 6
	s_and_b32 s98, s98, 0x1c0
	v_add_lshl_u32 v238, v208, s98, 2
	v_mov_b32_e32 v239, 0
	s_nop 0
	v_lshl_add_u64 v[232:233], s[100:101], 0, v[238:239]
	s_mov_b64 s[100:101], 0x2000
	v_lshl_add_u64 v[234:235], v[232:233], 0, s[100:101]
	s_mov_b64 s[100:101], 0x3800
	v_lshl_add_u64 v[236:237], v[232:233], 0, s[100:101]
	global_load_dword v224, v[232:233], off
	global_load_dword v225, v[232:233], off offset:2048
	global_load_dword v226, v[234:235], off offset:-4096
	global_load_dword v227, v[234:235], off
	global_load_dword v228, v[234:235], off offset:2048
	global_load_dword v229, v[236:237], off offset:-2048
	global_load_dword v230, v[236:237], off
	global_load_dword v231, v[236:237], off offset:2048
	s_waitcnt lgkmcnt(0)
	s_barrier
	ds_read_b128 v[36:39], v137
	ds_read_b128 v[44:47], v137 offset:64
	ds_read_b128 v[40:43], v137 offset:8192
	v_add_u32_e32 v52, s33, v111
	s_mov_b32 s68, s12
	s_waitcnt lgkmcnt(2)
	v_mfma_f32_16x16x32_bf16 v[36:39], v[0:3], v[36:39], 0
	v_readlane_b32 s12, v254, 2
	s_add_i32 s14, s68, s12
	s_lshl_b32 s14, s14, 6
	s_waitcnt lgkmcnt(1)
	v_mfma_f32_16x16x32_bf16 v[36:39], v[4:7], v[44:47], v[36:39]
	ds_read_b128 v[44:47], v137 offset:8256
	s_and_b32 s14, s14, 0x1c0
	s_add_i32 s66, s11, s14
	s_waitcnt lgkmcnt(1)
	v_mfma_f32_16x16x32_bf16 v[40:43], v[8:11], v[40:43], 0
	ds_read_b128 v[76:79], v138 offset:4096
	v_add_u32_e32 v191, s6, v125
	v_readlane_b32 s13, v254, 3
	s_waitcnt lgkmcnt(1)
	v_mfma_f32_16x16x32_bf16 v[40:43], v[12:15], v[44:47], v[40:43]
	ds_read_b128 v[44:47], v138
	s_mov_b32 s64, s12
	s_add_i32 s12, s68, 1
	s_waitcnt lgkmcnt(0)
	v_mfma_f32_16x16x32_bf16 v[44:47], v[16:19], v[44:47], 0
	ds_read_b128 v[84:87], v139 offset:64
	s_add_i32 s13, s12, s64
	v_add_u32_e32 v96, s6, v124
	v_mfma_f32_16x16x32_bf16 v[44:47], v[20:23], v[76:79], v[44:47]
	ds_read_b128 v[76:79], v138 offset:8192
	ds_read_b128 v[80:83], v139 offset:8192
	v_add_u32_e32 v93, s7, v123
	s_waitcnt lgkmcnt(1)
	v_mfma_f32_16x16x32_bf16 v[44:47], v[24:27], v[76:79], v[44:47]
	ds_read_b128 v[76:79], v138 offset:12288
	ds_read_b128 v[88:91], v140 offset:4096
	v_add_u32_e32 v97, s7, v124
	s_waitcnt lgkmcnt(1)
	v_mfma_f32_16x16x32_bf16 v[44:47], v[28:31], v[76:79], v[44:47]
	ds_read_b128 v[76:79], v138 offset:16384
	v_add_u32_e32 v192, s7, v125
	v_lshlrev_b32_e32 v197, 16, v162
	s_waitcnt lgkmcnt(0)
	v_mfma_f32_16x16x32_bf16 v[44:47], v[32:35], v[76:79], v[44:47]
	ds_read_b128 v[76:79], v139
	v_and_b32_e32 v199, 0xffff0000, v172
	s_ashr_i32 s67, s66, 31
	s_waitcnt lgkmcnt(0)
	v_mfma_f32_16x16x32_bf16 v[76:79], v[0:3], v[76:79], 0
	s_and_b32 s13, s13, 7
	v_mfma_f32_16x16x32_bf16 v[76:79], v[4:7], v[84:87], v[76:79]
	ds_read_b128 v[84:87], v139 offset:8256
	v_mfma_f32_16x16x32_bf16 v[80:83], v[8:11], v[80:83], 0
	s_waitcnt lgkmcnt(0)
	v_mfma_f32_16x16x32_bf16 v[80:83], v[12:15], v[84:87], v[80:83]
	ds_read_b128 v[84:87], v140
	s_waitcnt lgkmcnt(0)
	v_mfma_f32_16x16x32_bf16 v[84:87], v[16:19], v[84:87], 0
	v_mfma_f32_16x16x32_bf16 v[84:87], v[20:23], v[88:91], v[84:87]
	ds_read_b128 v[88:91], v140 offset:8192
	s_waitcnt lgkmcnt(0)
	v_mfma_f32_16x16x32_bf16 v[84:87], v[24:27], v[88:91], v[84:87]
	ds_read_b128 v[88:91], v140 offset:12288
	s_waitcnt lgkmcnt(0)
	v_mfma_f32_16x16x32_bf16 v[84:87], v[28:31], v[88:91], v[84:87]
	ds_read_b128 v[88:91], v140 offset:16384
	s_waitcnt lgkmcnt(0)
	s_barrier
	ds_write_b32 v52, v36
	v_add_u32_e32 v36, s6, v111
	ds_write_b32 v36, v40
	v_add_u32_e32 v36, s7, v111
	ds_write_b32 v36, v44
	v_add_u32_e32 v36, s33, v112
	ds_write_b32 v36, v37
	v_add_u32_e32 v36, s6, v112
	ds_write_b32 v36, v41
	v_add_u32_e32 v36, s7, v112
	ds_write_b32 v36, v45
	v_add_u32_e32 v36, s33, v113
	ds_write_b32 v36, v38
	v_add_u32_e32 v36, s6, v113
	ds_write_b32 v36, v42
	v_add_u32_e32 v36, s7, v113
	ds_write_b32 v36, v46
	v_add_u32_e32 v36, s33, v114
	ds_write_b32 v36, v39
	v_add_u32_e32 v36, s6, v114
	s_waitcnt lgkmcnt(10)
	v_mfma_f32_16x16x32_bf16 v[84:87], v[32:35], v[88:91], v[84:87]
	ds_write_b32 v36, v43
	v_add_u32_e32 v36, s7, v114
	ds_write_b32 v36, v47
	v_add_u32_e32 v36, s33, v115
	ds_write_b32 v36, v76
	v_add_u32_e32 v36, s6, v115
	ds_write_b32 v36, v80
	v_add_u32_e32 v36, s7, v115
	ds_write_b32 v36, v84
	v_add_u32_e32 v36, s33, v116
	ds_write_b32 v36, v77
	v_add_u32_e32 v36, s6, v116
	ds_write_b32 v36, v81
	v_add_u32_e32 v36, s7, v116
	ds_write_b32 v36, v85
	v_add_u32_e32 v36, s33, v117
	ds_write_b32 v36, v78
	v_add_u32_e32 v36, s6, v117
	ds_write_b32 v36, v82
	v_add_u32_e32 v36, s7, v117
	ds_write_b32 v36, v86
	v_add_u32_e32 v36, s33, v118
	ds_write_b32 v36, v79
	v_add_u32_e32 v36, s6, v118
	ds_write_b32 v36, v83
	v_add_u32_e32 v36, s7, v118
	ds_write_b32 v36, v87
	v_add_u32_e32 v36, s14, v208
	v_ashrrev_i32_e32 v37, 31, v36
	v_readlane_b32 s14, v254, 20
	v_lshlrev_b64 v[36:37], 2, v[36:37]
	v_readlane_b32 s15, v254, 21
	s_waitcnt lgkmcnt(0)
	s_barrier
; #define LAS __attribute__((address_space(3)))
; __device__ __forceinline__ float sigmoidf_(float x) { return __builtin_amdgcn_rcpf(1.0f + __expf(-x)); }
; __device__ __forceinline__ void rwkv_chunk_group(Frame& F, int bc, unsigned long long& tsub) {
;     ...
;         const float mur = mu[gc], muk = mu[512 + gc], muv = mu[1024 + gc];
;         const float w0 = (PRM + 2048)[gc], a0 = (PRM + 2560)[gc], k_k = (PRM + 3072)[gc], k_a = (PRM + 3584)[gc], r_k = (PRM + 4096)[gc];
;         float rr[8], kp[8], vv[8], aa[8], bb[8], ld[8], vbv[8], ggv[8];
;         float pr = bf2f(raw[0][0]), pk = bf2f(raw[0][1]), pv = bf2f(raw[0][2]);
;         bf16* VBp = (bf16*)(F.ws + WS_VB) + (size_t)item * 4096; bf16* Gp = (bf16*)(F.ws + WS_G) + (size_t)item * 4096;
;         float run = 0.f; float kkv[8], icv[8], sq[8], bq[8];
; #pragma unroll
;         for (int tt = 0; tt < 8; ++tt) { const int t = tb + tt;
;             const float cr = bf2f(raw[tt + 1][0]), ck = bf2f(raw[tt + 1][1]), cv = bf2f(raw[tt + 1][2]);
;             const float r = cr + (pr - cr) * mur, k = ck + (pk - ck) * muk, v = cv + (pv - cv) * muv; pr = cr; pk = ck; pv = cv;
;             const float wl = *(const LAS float*)(L + L_WL + (t * 65 + ch) * 4), al = *(const LAS float*)(L + L_AL + (t * 65 + ch) * 4), gl = *(const LAS float*)(L + L_GL + (t * 65 + ch) * 4);
;             const float z = -(w0 + wl); const float sp = fmaxf(z, 0.f) + __logf(1.f + __expf(-fabsf(z)));
;             const float lgd = -__expf(-sp - 0.5f);
;             const float ic = sigmoidf_(a0 + al);
;             const float kv = k * k_k; const float kq = k * (1.f + (ic - 1.f) * k_a);
;             kkv[tt] = kv; icv[tt] = ic; sq[tt] = kv * kv; bq[tt] = r * kq * r_k;
;             rr[tt] = r; kp[tt] = kq; vv[tt] = v; run += lgd; ld[tt] = run; ggv[tt] = gl;
;         }
	v_add_u32_e32 v41, s7, v120
	v_add_u32_e32 v87, s7, v122
	v_lshl_add_u64 v[38:39], s[14:15], 0, v[36:37]
	s_waitcnt vmcnt(0)
	v_mov_b32_e32 v95, v224
	v_mov_b32_e32 v42, v225
	s_movk_i32 s14, 0x1000
	v_add_co_u32_e32 v38, vcc, s14, v38
	v_readlane_b32 s14, v254, 29
	s_nop 0
	v_addc_co_u32_e32 v39, vcc, 0, v39, vcc
	v_readlane_b32 s15, v254, 30
	v_mov_b32_e32 v52, v226
	v_add_u32_e32 v83, s7, v121
	v_lshl_add_u64 v[38:39], s[14:15], 0, v[36:37]
	v_mov_b32_e32 v45, v227
	v_readlane_b32 s14, v254, 31
	v_readlane_b32 s15, v254, 32
	v_lshlrev_b32_e32 v82, 16, v155
	v_and_b32_e32 v77, 0xffff0000, v167
	v_lshl_add_u64 v[38:39], s[14:15], 0, v[36:37]
	v_mov_b32_e32 v43, v228
	v_readlane_b32 s14, v254, 33
	v_readlane_b32 s15, v254, 34
	v_lshlrev_b32_e32 v76, 16, v167
	v_and_b32_e32 v79, 0xffff0000, v166
	v_lshl_add_u64 v[38:39], s[14:15], 0, v[36:37]
	v_readlane_b32 s14, v254, 35
	v_readlane_b32 s15, v254, 36
	v_mov_b32_e32 v44, v229
	v_lshlrev_b32_e32 v78, 16, v166
	v_lshl_add_u64 v[38:39], s[14:15], 0, v[36:37]
	v_mov_b32_e32 v46, v230
	v_readlane_b32 s14, v254, 37
	v_readlane_b32 s15, v254, 38
	v_lshlrev_b32_e32 v86, 16, v157
	v_and_b32_e32 v91, 0xffff0000, v168
	v_lshl_add_u64 v[36:37], s[14:15], 0, v[36:37]
	v_mov_b32_e32 v103, v231
	v_lshlrev_b32_e32 v36, 16, v153
	v_lshlrev_b32_e32 v37, 16, v154
	v_sub_f32_e32 v36, v36, v37
	v_add_u32_e32 v38, s6, v119
	v_add_u32_e32 v39, s7, v119
	ds_read_b32 v38, v38
	ds_read_b32 v47, v39
	ds_read_b32 v177, v41
	ds_read_b32 v185, v87
	ds_read_b32 v191, v191
	v_lshlrev_b32_e32 v90, 16, v168
	v_and_b32_e32 v85, 0xffff0000, v169
	ds_read_b32 v182, v83
	ds_read_b32 v96, v96
	ds_read_b32 v189, v93
	ds_read_b32 v193, v97
	ds_read_b32 v194, v192
	s_waitcnt vmcnt(7)
	v_fma_f32 v173, v36, v95, v37
	v_add_u32_e32 v36, s33, v119
	ds_read_b32 v36, v36
	s_waitcnt vmcnt(4) lgkmcnt(0)
	v_add_f32_e32 v36, v45, v36
	v_max_f32_e64 v39, -v36, 0
	v_mul_f32_e64 v36, |v36|, s1
	v_exp_f32_e32 v36, v36
	s_nop 0
	v_add_f32_e32 v36, 1.0, v36
	v_cmp_gt_f32_e32 vcc, s8, v36
	s_nop 1
	v_cndmask_b32_e64 v40, 0, 32, vcc
	v_ldexp_f32 v36, v36, v40
	v_log_f32_e32 v36, v36
	s_nop 0
	v_mul_f32_e32 v40, 0x3f317217, v36
	v_fma_f32 v40, v36, s9, -v40
	v_fmac_f32_e32 v40, 0x3377d1cf, v36
	v_fmac_f32_e32 v40, 0x3f317217, v36
	v_cmp_lt_f32_e64 s[64:65], |v36|, s10
	s_nop 1
	v_cndmask_b32_e64 v36, v36, v40, s[64:65]
	v_cndmask_b32_e32 v40, 0, v147, vcc
	v_sub_f32_e32 v36, v36, v40
	v_add_f32_e32 v36, v39, v36
	v_add_u32_e32 v39, s33, v120
	ds_read_b32 v39, v39
	v_sub_f32_e32 v36, -0.5, v36
	v_mul_f32_e32 v36, 0x3fb8aa3b, v36
	v_exp_f32_e32 v102, v36
	s_waitcnt vmcnt(3)
	v_add_f32_e32 v36, v43, v38
	v_mul_f32_e32 v36, 0xbfb8aa3b, v36
	v_add_u32_e32 v40, s6, v120
	v_exp_f32_e32 v36, v36
	ds_read_b32 v40, v40
	s_waitcnt lgkmcnt(1)
	v_add_f32_e32 v39, v45, v39
	v_max_f32_e64 v41, -v39, 0
	v_mul_f32_e64 v39, |v39|, s1
	v_exp_f32_e32 v39, v39
	v_add_f32_e32 v36, 1.0, v36
	v_rcp_f32_e32 v38, v36
	v_sub_f32_e32 v36, v37, v82
	v_fma_f32 v174, v36, v95, v82
	v_and_b32_e32 v37, 0xffff0000, v161
	v_lshlrev_b32_e32 v36, 16, v161
	v_add_f32_e32 v39, 1.0, v39
	v_pk_add_f32 v[36:37], v[36:37], v[76:77] neg_lo:[0,1] neg_hi:[0,1]
	v_cmp_gt_f32_e32 vcc, s8, v39
	v_pk_fma_f32 v[36:37], v[36:37], v[52:53], v[76:77] op_sel_hi:[1,0,1]
	s_nop 0
	v_cndmask_b32_e64 v76, 0, 32, vcc
	v_ldexp_f32 v39, v39, v76
	v_log_f32_e32 v39, v39
	s_nop 0
	v_mul_f32_e32 v76, 0x3f317217, v39
	v_fma_f32 v76, v39, s9, -v76
	v_fmac_f32_e32 v76, 0x3377d1cf, v39
	v_fmac_f32_e32 v76, 0x3f317217, v39
	v_cmp_lt_f32_e64 s[64:65], |v39|, s10
	s_nop 1
	v_cndmask_b32_e64 v39, v39, v76, s[64:65]
	v_cndmask_b32_e32 v76, 0, v147, vcc
	v_sub_f32_e32 v39, v39, v76
	v_add_f32_e32 v39, v41, v39
	v_sub_f32_e32 v39, -0.5, v39
	v_mul_f32_e32 v39, 0x3fb8aa3b, v39
	v_exp_f32_e32 v76, v39
	s_waitcnt lgkmcnt(0)
	v_add_f32_e32 v39, v43, v40
	v_mul_f32_e32 v39, 0xbfb8aa3b, v39
	v_exp_f32_e32 v39, v39
	v_and_b32_e32 v41, 0xffff0000, v160
	v_lshlrev_b32_e32 v40, 16, v160
	v_pk_add_f32 v[40:41], v[40:41], v[78:79] neg_lo:[0,1] neg_hi:[0,1]
	v_add_f32_e32 v39, 1.0, v39
	v_rcp_f32_e32 v39, v39
	v_pk_fma_f32 v[80:81], v[40:41], v[42:43], v[78:79] op_sel_hi:[1,0,1]
	v_sub_f32_e64 v176, -v102, v76
	v_lshlrev_b32_e32 v76, 16, v156
	v_pk_add_f32 v[40:41], v[38:39], -1.0 op_sel_hi:[1,0]
	s_waitcnt vmcnt(1)
	v_pk_fma_f32 v[40:41], v[46:47], v[40:41], 1.0 op_sel_hi:[0,1,0]
	v_pk_mul_f32 v[40:41], v[80:81], v[40:41]
	s_nop 0
	v_mul_f32_e32 v78, v173, v40
	s_waitcnt vmcnt(0)
	v_mul_f32_e32 v101, v103, v78
	v_mul_f32_e32 v78, v174, v41
	v_mul_f32_e32 v100, v103, v78
	v_sub_f32_e32 v78, v82, v76
	v_fma_f32 v175, v78, v95, v76
	v_add_u32_e32 v78, s33, v121
	ds_read_b32 v78, v78
	v_add_u32_e32 v82, s6, v121
	ds_read_b32 v82, v82
	v_sub_f32_e32 v76, v76, v86
	v_fma_f32 v178, v76, v95, v86
	s_waitcnt lgkmcnt(1)
	v_add_f32_e32 v78, v45, v78
	v_max_f32_e64 v83, -v78, 0
	v_mul_f32_e64 v78, |v78|, s1
	v_exp_f32_e32 v78, v78
	s_waitcnt lgkmcnt(0)
	v_add_f32_e32 v82, v43, v82
	v_mul_f32_e32 v82, 0xbfb8aa3b, v82
	v_exp_f32_e32 v82, v82
	v_add_f32_e32 v78, 1.0, v78
	v_cmp_gt_f32_e32 vcc, s8, v78
	v_add_f32_e32 v82, 1.0, v82
	s_nop 0
	v_cndmask_b32_e64 v84, 0, 32, vcc
	v_ldexp_f32 v78, v78, v84
	v_log_f32_e32 v78, v78
	v_rcp_f32_e32 v82, v82
	v_mul_f32_e32 v84, 0x3f317217, v78
	v_fma_f32 v84, v78, s9, -v84
	v_fmac_f32_e32 v84, 0x3377d1cf, v78
	v_fmac_f32_e32 v84, 0x3f317217, v78
	v_cmp_lt_f32_e64 s[64:65], |v78|, s10
	s_nop 1
	v_cndmask_b32_e64 v78, v78, v84, s[64:65]
	v_cndmask_b32_e32 v84, 0, v147, vcc
	v_sub_f32_e32 v78, v78, v84
	v_add_f32_e32 v78, v83, v78
	v_sub_f32_e32 v78, -0.5, v78
	v_mul_f32_e32 v78, 0x3fb8aa3b, v78
	v_exp_f32_e32 v78, v78
	v_add_u32_e32 v83, s6, v122
	ds_read_b32 v83, v83
	v_lshlrev_b32_e32 v84, 16, v169
	v_sub_f32_e32 v179, v176, v78
	v_add_u32_e32 v78, s33, v122
	ds_read_b32 v78, v78
	v_pk_mov_b32 v[76:77], v[76:77], v[84:85] op_sel:[1,0]
	s_waitcnt lgkmcnt(0)
; #define LAS __attribute__((address_space(3)))
; __device__ __forceinline__ float sigmoidf_(float x) { return __builtin_amdgcn_rcpf(1.0f + __expf(-x)); }
; __device__ __forceinline__ void rwkv_chunk_group(Frame& F, int bc, unsigned long long& tsub) {
;     ...
;         for (int tt = 0; tt < 8; ++tt) { const int t = tb + tt;
;             const float cr = bf2f(raw[tt + 1][0]), ck = bf2f(raw[tt + 1][1]), cv = bf2f(raw[tt + 1][2]);
;             const float r = cr + (pr - cr) * mur, k = ck + (pk - ck) * muk, v = cv + (pv - cv) * muv; pr = cr; pk = ck; pv = cv;
;             const float wl = *(const LAS float*)(L + L_WL + (t * 65 + ch) * 4), al = *(const LAS float*)(L + L_AL + (t * 65 + ch) * 4), gl = *(const LAS float*)(L + L_GL + (t * 65 + ch) * 4);
;             const float z = -(w0 + wl); const float sp = fmaxf(z, 0.f) + __logf(1.f + __expf(-fabsf(z)));
;             const float lgd = -__expf(-sp - 0.5f);
;             const float ic = sigmoidf_(a0 + al);
;             const float kv = k * k_k; const float kq = k * (1.f + (ic - 1.f) * k_a);
;             kkv[tt] = kv; icv[tt] = ic; sq[tt] = kv * kv; bq[tt] = r * kq * r_k;
;             rr[tt] = r; kp[tt] = kq; vv[tt] = v; run += lgd; ld[tt] = run; ggv[tt] = gl;
;         }
;         wave_sum8(sq); wave_sum8(bq);
	v_add_f32_e32 v78, v45, v78
	v_max_f32_e64 v87, -v78, 0
	v_mul_f32_e64 v78, |v78|, s1
	v_exp_f32_e32 v78, v78
	v_pk_add_f32 v[76:77], v[76:77], v[84:85] neg_lo:[0,1] neg_hi:[0,1]
	v_add_f32_e32 v78, 1.0, v78
	v_cmp_gt_f32_e32 vcc, s8, v78
	v_pk_fma_f32 v[76:77], v[76:77], v[52:53], v[84:85] op_sel_hi:[1,0,1]
	s_nop 0
	v_cndmask_b32_e64 v88, 0, 32, vcc
	v_ldexp_f32 v78, v78, v88
	v_log_f32_e32 v78, v78
	s_nop 0
	v_mul_f32_e32 v88, 0x3f317217, v78
	v_fma_f32 v88, v78, s9, -v88
	v_fmac_f32_e32 v88, 0x3377d1cf, v78
	v_fmac_f32_e32 v88, 0x3f317217, v78
	v_cmp_lt_f32_e64 s[64:65], |v78|, s10
	s_nop 1
	v_cndmask_b32_e64 v78, v78, v88, s[64:65]
	v_cndmask_b32_e32 v88, 0, v147, vcc
	v_sub_f32_e32 v78, v78, v88
	v_add_f32_e32 v78, v87, v78
	v_sub_f32_e32 v78, -0.5, v78
	v_mul_f32_e32 v78, 0x3fb8aa3b, v78
	v_exp_f32_e32 v87, v78
	v_add_f32_e32 v78, v43, v83
	v_mul_f32_e32 v78, 0xbfb8aa3b, v78
	v_exp_f32_e32 v78, v78
	v_sub_f32_e32 v181, v179, v87
	v_lshlrev_b32_e32 v87, 16, v158
	v_sub_f32_e32 v86, v86, v87
	v_add_f32_e32 v78, 1.0, v78
	v_rcp_f32_e32 v83, v78
	v_pk_mov_b32 v[78:79], v[78:79], v[90:91] op_sel:[1,0]
	v_fma_f32 v180, v86, v95, v87
	v_pk_add_f32 v[78:79], v[78:79], v[90:91] neg_lo:[0,1] neg_hi:[0,1]
	v_add_u32_e32 v86, s33, v123
	v_pk_fma_f32 v[88:89], v[78:79], v[42:43], v[90:91] op_sel_hi:[1,0,1]
	v_pk_add_f32 v[78:79], v[82:83], -1.0 op_sel_hi:[1,0]
	ds_read_b32 v86, v86
	v_pk_fma_f32 v[78:79], v[46:47], v[78:79], 1.0 op_sel_hi:[0,1,0]
	v_pk_mul_f32 v[78:79], v[88:89], v[78:79]
	s_nop 0
	v_mul_f32_e32 v92, v175, v78
	v_mul_f32_e32 v187, v103, v92
	v_mul_f32_e32 v92, v178, v79
	v_mul_f32_e32 v186, v103, v92
	v_add_u32_e32 v92, s6, v123
	ds_read_b32 v92, v92
	s_waitcnt lgkmcnt(1)
	v_add_f32_e32 v86, v45, v86
	v_max_f32_e64 v93, -v86, 0
	v_mul_f32_e64 v86, |v86|, s1
	v_exp_f32_e32 v86, v86
	s_nop 0
	v_add_f32_e32 v86, 1.0, v86
	v_cmp_gt_f32_e32 vcc, s8, v86
	s_nop 1
	v_cndmask_b32_e64 v94, 0, 32, vcc
	v_ldexp_f32 v86, v86, v94
	v_log_f32_e32 v86, v86
	s_nop 0
	v_mul_f32_e32 v94, 0x3f317217, v86
	v_fma_f32 v94, v86, s9, -v94
	v_fmac_f32_e32 v94, 0x3377d1cf, v86
	v_fmac_f32_e32 v94, 0x3f317217, v86
	v_cmp_lt_f32_e64 s[64:65], |v86|, s10
	s_nop 1
	v_cndmask_b32_e64 v86, v86, v94, s[64:65]
	v_cndmask_b32_e32 v94, 0, v147, vcc
	v_sub_f32_e32 v86, v86, v94
	v_lshlrev_b32_e32 v94, 16, v159
	v_sub_f32_e32 v87, v87, v94
	v_fma_f32 v183, v87, v95, v94
	v_add_u32_e32 v87, s33, v124
	ds_read_b32 v87, v87
	v_add_f32_e32 v86, v93, v86
	v_sub_f32_e32 v86, -0.5, v86
	v_mul_f32_e32 v86, 0x3fb8aa3b, v86
	v_exp_f32_e32 v93, v86
	s_waitcnt lgkmcnt(0)
	v_add_f32_e32 v87, v45, v87
	v_max_f32_e64 v97, -v87, 0
	v_mul_f32_e64 v87, |v87|, s1
	v_exp_f32_e32 v87, v87
	v_add_f32_e32 v86, v43, v92
	v_mul_f32_e32 v86, 0xbfb8aa3b, v86
	v_exp_f32_e32 v86, v86
	v_add_f32_e32 v87, 1.0, v87
	v_cmp_gt_f32_e32 vcc, s8, v87
	v_sub_f32_e32 v184, v181, v93
	v_add_f32_e32 v86, 1.0, v86
	v_cndmask_b32_e64 v98, 0, 32, vcc
	v_ldexp_f32 v87, v87, v98
	v_log_f32_e32 v87, v87
	v_rcp_f32_e32 v86, v86
	v_sub_f32_e32 v94, v94, v197
	v_and_b32_e32 v93, 0xffff0000, v171
	v_mul_f32_e32 v98, 0x3f317217, v87
	v_fma_f32 v98, v87, s9, -v98
	v_fmac_f32_e32 v98, 0x3377d1cf, v87
	v_fmac_f32_e32 v98, 0x3f317217, v87
	v_cmp_lt_f32_e64 s[64:65], |v87|, s10
	v_lshlrev_b32_e32 v92, 16, v171
	v_pk_mov_b32 v[84:85], v[84:85], v[92:93] op_sel:[1,0]
	v_cndmask_b32_e64 v87, v87, v98, s[64:65]
	v_cndmask_b32_e32 v98, 0, v147, vcc
	v_sub_f32_e32 v87, v87, v98
	v_add_f32_e32 v87, v97, v87
	v_sub_f32_e32 v87, -0.5, v87
	v_mul_f32_e32 v87, 0x3fb8aa3b, v87
	v_exp_f32_e32 v188, v87
	v_add_f32_e32 v87, v43, v96
	v_mul_f32_e32 v87, 0xbfb8aa3b, v87
	v_exp_f32_e32 v87, v87
	v_and_b32_e32 v97, 0xffff0000, v170
	v_lshlrev_b32_e32 v96, 16, v170
	v_pk_mov_b32 v[90:91], v[90:91], v[96:97] op_sel:[1,0]
	v_add_f32_e32 v87, 1.0, v87
	v_rcp_f32_e32 v87, v87
	v_pk_add_f32 v[90:91], v[90:91], v[96:97] neg_lo:[0,1] neg_hi:[0,1]
	v_pk_add_f32 v[84:85], v[84:85], v[92:93] neg_lo:[0,1] neg_hi:[0,1]
	v_pk_fma_f32 v[98:99], v[90:91], v[42:43], v[96:97] op_sel_hi:[1,0,1]
	v_pk_add_f32 v[90:91], v[86:87], -1.0 op_sel_hi:[1,0]
	v_pk_fma_f32 v[84:85], v[84:85], v[52:53], v[92:93] op_sel_hi:[1,0,1]
	v_pk_fma_f32 v[90:91], v[46:47], v[90:91], 1.0 op_sel_hi:[0,1,0]
	v_pk_mul_f32 v[90:91], v[98:99], v[90:91]
	s_nop 0
	v_mul_f32_e32 v190, v180, v90
	v_mul_f32_e32 v196, v103, v190
	v_mul_f32_e32 v190, v183, v91
	v_mul_f32_e32 v195, v103, v190
	v_sub_f32_e32 v190, v184, v188
	v_fma_f32 v188, v94, v95, v197
	v_add_u32_e32 v94, s33, v125
	ds_read_b32 v94, v94
	v_permlane32_swap_b32_e32 v101, v196
	v_permlane32_swap_b32_e32 v100, v195
	s_waitcnt lgkmcnt(0)
	v_add_f32_e32 v94, v45, v94
	v_max_f32_e64 v192, -v94, 0
	v_mul_f32_e64 v94, |v94|, s1
	v_exp_f32_e32 v94, v94
	v_add_f32_e32 v201, v101, v196
	v_add_f32_e32 v195, v100, v195
	v_add_f32_e32 v94, 1.0, v94
	v_cmp_gt_f32_e32 vcc, s8, v94
	s_nop 1
	v_cndmask_b32_e64 v198, 0, 32, vcc
	v_ldexp_f32 v94, v94, v198
	v_log_f32_e32 v94, v94
	s_nop 0
	v_mul_f32_e32 v198, 0x3f317217, v94
	v_fma_f32 v198, v94, s9, -v198
	v_fmac_f32_e32 v198, 0x3377d1cf, v94
	v_fmac_f32_e32 v198, 0x3f317217, v94
	v_cmp_lt_f32_e64 s[64:65], |v94|, s10
	s_nop 1
	v_cndmask_b32_e64 v94, v94, v198, s[64:65]
	v_cndmask_b32_e32 v198, 0, v147, vcc
	v_sub_f32_e32 v94, v94, v198
	v_lshlrev_b32_e32 v198, 16, v172
	v_pk_mov_b32 v[92:93], v[92:93], v[198:199] op_sel:[1,0]
	v_add_f32_e32 v94, v192, v94
	v_pk_add_f32 v[92:93], v[92:93], v[198:199] neg_lo:[0,1] neg_hi:[0,1]
	v_sub_f32_e32 v94, -0.5, v94
	v_pk_fma_f32 v[92:93], v[92:93], v[52:53], v[198:199] op_sel_hi:[1,0,1]
	v_add_u32_e32 v52, s33, v126
	ds_read_b32 v52, v52
	v_mul_f32_e32 v94, 0x3fb8aa3b, v94
	v_exp_f32_e32 v192, v94
	v_add_f32_e32 v94, v43, v191
	v_lshlrev_b32_e32 v191, 16, v163
	v_sub_f32_e32 v197, v197, v191
	v_fmac_f32_e32 v191, v197, v95
	v_add_u32_e32 v95, s6, v126
	v_add_u32_e32 v197, s7, v126
	ds_read_b32 v95, v95
	ds_read_b32 v200, v197
	s_waitcnt lgkmcnt(2)
; #define GAS __attribute__((address_space(1)))
; #define LAS __attribute__((address_space(3)))
; __device__ __forceinline__ unsigned pk2(float lo, float hi) { f32x2_k v = {lo, hi}; bf16x2_k b = __builtin_convertvector(v, bf16x2_k); return __builtin_bit_cast(unsigned, b); }
; __device__ __forceinline__ void rwkv_chunk_group(Frame& F, int bc, unsigned long long& tsub) {
;     ...
;         wave_sum8(sq); wave_sum8(bq);
; #pragma unroll
;         for (int tt = 0; tt < 8; ++tt) { const float kn = kkv[tt] * __builtin_amdgcn_rsqf(fmaxf(sq[tt], 1e-24f));
;             aa[tt] = -kn; bb[tt] = kn * icv[tt]; vbv[tt] = bq[tt] * vv[tt]; }
;         *(LAS float*)(L + L_GT + (w * 64 + ch) * 4) = run;
;         *(GAS v4u*)(VBp + ch * 64 + tb) = (v4u){pk2(vbv[0], vbv[1]), pk2(vbv[2], vbv[3]), pk2(vbv[4], vbv[5]), pk2(vbv[6], vbv[7])};
;         *(GAS v4u*)(Gp + ch * 64 + tb) = (v4u){pk2(ggv[0], ggv[1]), pk2(ggv[2], ggv[3]), pk2(ggv[4], ggv[5]), pk2(ggv[6], ggv[7])};
;         if (hh + 1 < RW_H) {
;             const bool has = (c * CH + tb > 0);
; #pragma unroll
;             for (int tt = 0; tt < 9; ++tt) { const size_t off = (size_t)(row0 + tb + tt - 1) * PRW + hnext * 64 + ch;
;                 if (tt > 0 || has) { raw[tt][0] = P[off]; raw[tt][1] = P[off + 512]; raw[tt][2] = P[off + 1024]; } }
	v_add_f32_e32 v45, v45, v52
	v_max_f32_e64 v52, -v45, 0
	v_mul_f32_e64 v45, |v45|, s1
	v_exp_f32_e32 v45, v45
	s_waitcnt lgkmcnt(1)
	v_add_f32_e32 v43, v43, v95
	v_mul_f32_e32 v94, 0xbfb8aa3b, v94
	v_mul_f32_e32 v43, 0xbfb8aa3b, v43
	v_add_f32_e32 v45, 1.0, v45
	v_cmp_gt_f32_e32 vcc, s8, v45
	v_exp_f32_e32 v94, v94
	v_exp_f32_e32 v43, v43
	v_cndmask_b32_e64 v197, 0, 32, vcc
	v_ldexp_f32 v45, v45, v197
	v_log_f32_e32 v45, v45
	v_add_f32_e32 v94, 1.0, v94
	v_add_f32_e32 v43, 1.0, v43
	v_rcp_f32_e32 v94, v94
	v_mul_f32_e32 v197, 0x3f317217, v45
	v_fma_f32 v197, v45, s9, -v197
	v_fmac_f32_e32 v197, 0x3377d1cf, v45
	v_fmac_f32_e32 v197, 0x3f317217, v45
	v_cmp_lt_f32_e64 s[64:65], |v45|, s10
	v_rcp_f32_e32 v95, v43
	v_sub_f32_e32 v192, v190, v192
	v_cndmask_b32_e64 v45, v45, v197, s[64:65]
	v_cndmask_b32_e32 v197, 0, v147, vcc
	v_sub_f32_e32 v45, v45, v197
	v_add_f32_e32 v45, v52, v45
	v_sub_f32_e32 v45, -0.5, v45
	v_mul_f32_e32 v45, 0x3fb8aa3b, v45
	v_exp_f32_e32 v45, v45
	s_nop 0
	v_pk_mul_f32 v[100:101], v[80:81], v[44:45] op_sel_hi:[1,0]
	v_pk_mul_f32 v[80:81], v[98:99], v[44:45] op_sel_hi:[1,0]
	v_pk_mul_f32 v[196:197], v[100:101], v[100:101]
	v_pk_mul_f32 v[98:99], v[80:81], v[80:81]
	v_sub_f32_e32 v52, v192, v45
	s_nop 0
	v_permlane32_swap_b32_e32 v196, v98
	v_permlane32_swap_b32_e32 v197, v99
	v_add_f32_e32 v196, v196, v98
	v_add_f32_e32 v197, v197, v99
	v_lshlrev_b32_e32 v98, 16, v165
	v_and_b32_e32 v99, 0xffff0000, v165
	v_pk_mov_b32 v[96:97], v[96:97], v[98:99] op_sel:[1,0]
	v_pk_mul_f32 v[88:89], v[88:89], v[44:45] op_sel_hi:[1,0]
	v_pk_add_f32 v[96:97], v[96:97], v[98:99] neg_lo:[0,1] neg_hi:[0,1]
	v_pk_mul_f32 v[198:199], v[88:89], v[88:89]
	v_pk_fma_f32 v[42:43], v[96:97], v[42:43], v[98:99] op_sel_hi:[1,0,1]
	v_pk_add_f32 v[98:99], v[94:95], -1.0 op_sel_hi:[1,0]
	v_pk_mul_f32 v[44:45], v[42:43], v[44:45] op_sel_hi:[1,0]
	v_pk_fma_f32 v[98:99], v[46:47], v[98:99], 1.0 op_sel_hi:[0,1,0]
	v_pk_mul_f32 v[42:43], v[42:43], v[98:99]
	v_pk_mul_f32 v[96:97], v[44:45], v[44:45]
	v_mul_f32_e32 v46, v188, v42
	v_mul_f32_e32 v46, v103, v46
	s_nop 1
	v_permlane32_swap_b32_e32 v187, v46
	v_add_f32_e32 v46, v187, v46
	v_mul_f32_e32 v98, v191, v43
	s_nop 0
	v_permlane16_swap_b32_e32 v201, v46
	v_mul_f32_e32 v98, v103, v98
	v_add_f32_e32 v46, v201, v46
	s_nop 0
	v_permlane32_swap_b32_e32 v186, v98
	v_add_f32_dpp v46, v46, v46 quad_perm:[1,0,3,2] row_mask:0xf bank_mask:0xf bound_ctrl:1
	v_add_f32_e32 v98, v186, v98
	s_nop 1
	v_permlane16_swap_b32_e32 v195, v98
	v_add_f32_dpp v46, v46, v46 quad_perm:[2,3,0,1] row_mask:0xf bank_mask:0xf bound_ctrl:1
	v_add_f32_e32 v98, v195, v98
	v_permlane32_swap_b32_e32 v198, v96
	v_add_f32_dpp v46, v46, v46 row_half_mirror row_mask:0xf bank_mask:0xf bound_ctrl:1
	v_permlane32_swap_b32_e32 v199, v97
	s_nop 0
	v_add_f32_dpp v46, v46, v46 row_mirror row_mask:0xf bank_mask:0xf bound_ctrl:1
	v_add_f32_dpp v98, v98, v98 quad_perm:[1,0,3,2] row_mask:0xf bank_mask:0xf bound_ctrl:1
	v_readlane_b32 s14, v46, 0
	v_readlane_b32 s64, v46, 16
	v_readlane_b32 s72, v46, 32
	v_readlane_b32 s96, v46, 48
	v_add_f32_e32 v46, v198, v96
	v_add_f32_e32 v96, v199, v97
	v_add_f32_dpp v98, v98, v98 quad_perm:[2,3,0,1] row_mask:0xf bank_mask:0xf bound_ctrl:1
	v_permlane16_swap_b32_e32 v196, v46
	v_permlane16_swap_b32_e32 v197, v96
	v_add_f32_dpp v98, v98, v98 row_half_mirror row_mask:0xf bank_mask:0xf bound_ctrl:1
	v_add_f32_e32 v46, v196, v46
	v_add_f32_e32 v96, v197, v96
	v_add_f32_dpp v98, v98, v98 row_mirror row_mask:0xf bank_mask:0xf bound_ctrl:1
	v_add_f32_dpp v46, v46, v46 quad_perm:[1,0,3,2] row_mask:0xf bank_mask:0xf bound_ctrl:1
	v_add_f32_dpp v96, v96, v96 quad_perm:[1,0,3,2] row_mask:0xf bank_mask:0xf bound_ctrl:1
	v_readlane_b32 s73, v98, 32
	v_add_f32_dpp v46, v46, v46 quad_perm:[2,3,0,1] row_mask:0xf bank_mask:0xf bound_ctrl:1
	v_add_f32_dpp v96, v96, v96 quad_perm:[2,3,0,1] row_mask:0xf bank_mask:0xf bound_ctrl:1
	v_readlane_b32 s15, v98, 0
	v_readlane_b32 s65, v98, 16
	v_readlane_b32 s97, v98, 48
	v_add_f32_dpp v46, v46, v46 row_half_mirror row_mask:0xf bank_mask:0xf bound_ctrl:1
	v_add_f32_dpp v96, v96, v96 row_half_mirror row_mask:0xf bank_mask:0xf bound_ctrl:1
	v_pk_mul_f32 v[196:197], v[84:85], s[72:73]
	s_lshl_b64 s[72:73], s[66:67], 13
	v_pk_mul_f32 v[98:99], v[36:37], s[14:15]
	v_pk_mul_f32 v[186:187], v[76:77], s[64:65]
	v_add_f32_dpp v46, v46, v46 row_mirror row_mask:0xf bank_mask:0xf bound_ctrl:1
	v_add_f32_dpp v96, v96, v96 row_mirror row_mask:0xf bank_mask:0xf bound_ctrl:1
	v_pk_mul_f32 v[198:199], v[92:93], s[96:97]
	v_readlane_b32 s15, v254, 39
	s_cmp_eq_u32 s68, 7
	v_readlane_b32 s93, v46, 0
	v_readlane_b32 s71, v46, 16
	v_readlane_b32 s69, v46, 32
	v_readlane_b32 s64, v46, 48
	v_readlane_b32 s14, v96, 0
	v_readlane_b32 s77, v96, 16
	v_readlane_b32 s70, v96, 32
	v_readlane_b32 s65, v96, 48
	v_add_u32_e32 v46, s15, v105
	v_cvt_pk_bf16_f32 v96, v98, v99
	v_cvt_pk_bf16_f32 v97, v186, v187
	v_cvt_pk_bf16_f32 v98, v196, v197
	v_cvt_pk_bf16_f32 v99, v198, v199
	v_lshl_add_u64 v[186:187], v[62:63], 0, s[72:73]
	s_cselect_b64 s[96:97], -1, 0
	ds_write_b32 v46, v52
	global_store_dwordx4 v[186:187], v[96:99], off
	s_and_b64 vcc, exec, s[96:97]
	s_nop 0
	v_cvt_pk_bf16_f32 v96, v47, v177
	v_cvt_pk_bf16_f32 v97, v182, v185
	v_cvt_pk_bf16_f32 v98, v189, v193
	s_waitcnt lgkmcnt(1)
	v_cvt_pk_bf16_f32 v99, v194, v200
	v_lshl_add_u64 v[46:47], v[64:65], 0, s[72:73]
	global_store_dwordx4 v[46:47], v[96:99], off
	s_cbranch_vccnz .LBB0_1416
	v_readlane_b32 s72, v254, 60
	s_lshl_b32 s94, s13, 7
	v_readlane_b32 s73, v254, 61
	v_lshl_add_u64 v[46:47], v[56:57], 0, s[94:95]
	s_andn2_b64 vcc, exec, s[72:73]
	s_cbranch_vccnz .LBB0_1415
	v_readlane_b32 s72, v254, 62
	v_readlane_b32 s73, v254, 63
	s_nop 1
	v_lshl_add_u64 v[96:97], v[46:47], 0, s[72:73]
	global_load_ushort v153, v[96:97], off
	global_load_ushort v202, v[96:97], off offset:1024
	global_load_ushort v215, v[96:97], off offset:2048
; __device__ __forceinline__ void rwkv_chunk_group(Frame& F, int bc, unsigned long long& tsub) {
;     ...
;         if (hh + 1 < RW_H) {
;             const bool has = (c * CH + tb > 0);
; #pragma unroll
;             for (int tt = 0; tt < 9; ++tt) { const size_t off = (size_t)(row0 + tb + tt - 1) * PRW + hnext * 64 + ch;
;                 if (tt > 0 || has) { raw[tt][0] = P[off]; raw[tt][1] = P[off + 512]; raw[tt][2] = P[off + 1024]; } }
.LBB0_1415:
	v_readlane_b32 s72, v255, 0
	v_readlane_b32 s73, v255, 1
	s_nop 1
	v_lshl_add_u64 v[96:97], v[46:47], 0, s[72:73]
	v_readlane_b32 s72, v255, 2
	v_readlane_b32 s73, v255, 3
	global_load_ushort v154, v[96:97], off
	global_load_ushort v203, v[96:97], off offset:1024
	global_load_ushort v216, v[96:97], off offset:2048
	v_lshl_add_u64 v[96:97], v[46:47], 0, s[72:73]
	v_readlane_b32 s72, v255, 4
	v_readlane_b32 s73, v255, 5
	global_load_ushort v155, v[96:97], off
	global_load_ushort v204, v[96:97], off offset:1024
	global_load_ushort v217, v[96:97], off offset:2048
	v_lshl_add_u64 v[96:97], v[46:47], 0, s[72:73]
	v_readlane_b32 s72, v255, 6
	v_readlane_b32 s73, v255, 7
	global_load_ushort v156, v[96:97], off
	global_load_ushort v205, v[96:97], off offset:1024
	global_load_ushort v218, v[96:97], off offset:2048
	v_lshl_add_u64 v[96:97], v[46:47], 0, s[72:73]
	v_readlane_b32 s72, v255, 8
	v_readlane_b32 s73, v255, 9
	global_load_ushort v157, v[96:97], off
	global_load_ushort v206, v[96:97], off offset:1024
	global_load_ushort v219, v[96:97], off offset:2048
	v_lshl_add_u64 v[96:97], v[46:47], 0, s[72:73]
	v_readlane_b32 s72, v255, 10
	v_readlane_b32 s73, v255, 11
	global_load_ushort v158, v[96:97], off
	global_load_ushort v207, v[96:97], off offset:1024
	global_load_ushort v220, v[96:97], off offset:2048
	v_lshl_add_u64 v[96:97], v[46:47], 0, s[72:73]
	v_readlane_b32 s72, v255, 12
	v_readlane_b32 s73, v255, 13
	global_load_ushort v159, v[96:97], off
	global_load_ushort v212, v[96:97], off offset:1024
	global_load_ushort v221, v[96:97], off offset:2048
	v_lshl_add_u64 v[96:97], v[46:47], 0, s[72:73]
	v_readlane_b32 s72, v255, 14
	global_load_ushort v162, v[96:97], off
	global_load_ushort v213, v[96:97], off offset:1024
	s_nop 0
	global_load_ushort v222, v[96:97], off offset:2048
	v_readlane_b32 s73, v255, 15
	v_lshl_add_u64 v[46:47], v[46:47], 0, s[72:73]
	global_load_ushort v223, v[46:47], off offset:2048
	global_load_ushort v214, v[46:47], off offset:1024
	global_load_ushort v163, v[46:47], off

; #define GAS __attribute__((address_space(1)))
; #define LAS __attribute__((address_space(3)))
; __device__ __forceinline__ void rwkv_chunk_group(Frame& F, int bc, unsigned long long& tsub) {
;     ...
;         for (int tt = 0; tt < 8; ++tt) { const float kn = kkv[tt] * __builtin_amdgcn_rsqf(fmaxf(sq[tt], 1e-24f));
;             aa[tt] = -kn; bb[tt] = kn * icv[tt]; vbv[tt] = bq[tt] * vv[tt]; }
;         *(LAS float*)(L + L_GT + (w * 64 + ch) * 4) = run;
;         *(GAS v4u*)(VBp + ch * 64 + tb) = (v4u){pk2(vbv[0], vbv[1]), pk2(vbv[2], vbv[3]), pk2(vbv[4], vbv[5]), pk2(vbv[6], vbv[7])};
;         *(GAS v4u*)(Gp + ch * 64 + tb) = (v4u){pk2(ggv[0], ggv[1]), pk2(ggv[2], ggv[3]), pk2(ggv[4], ggv[5]), pk2(ggv[6], ggv[7])};
;         if (hh + 1 < RW_H) {
;             const bool has = (c * CH + tb > 0);
; #pragma unroll
;             for (int tt = 0; tt < 9; ++tt) { const size_t off = (size_t)(row0 + tb + tt - 1) * PRW + hnext * 64 + ch;
;                 if (tt > 0 || has) { raw[tt][0] = P[off]; raw[tt][1] = P[off + 512]; raw[tt][2] = P[off + 1024]; } }
;         }
;         LBAR();
;         float offs = 0.f, tot = 0.f;
; #pragma unroll
;         for (int g = 0; g < 8; ++g) { const float x = *(const LAS float*)(L + L_GT + (g * 64 + ch) * 4); if (g < w) offs += x; tot += x; }
;         const float etot = __expf(tot);
;         if (w == 0) *(LAS float*)(L + L_WC + ch * 4) = etot;
;         unsigned patt[4], pvt[4], pbh[4], pkh[4]; float hAt = 0.f, hBh = 0.f, hKh = 0.f;
;         float e_ex = __expf(offs);
; #pragma unroll
;         for (int tt = 0; tt < 8; ++tt) { const int t = tb + tt; const float cl = offs + ld[tt];
;             const float e_in = __expf(cl), e_inv = __builtin_amdgcn_rcpf(e_in), e_hat = etot * e_inv;
;             const float At = aa[tt] * e_ex, Bt = bb[tt] * e_inv, Kt = kp[tt] * e_inv, Rt = rr[tt] * e_in, Bh = bb[tt] * e_hat, Kh = kp[tt] * e_hat; e_ex = e_in;
;             *(LAS bf16*)(L + L_AT + t * LD + ch * 2) = (bf16)f2bf(At); *(LAS bf16*)(L + L_BT + t * LD + ch * 2) = (bf16)f2bf(Bt);
;             *(LAS bf16*)(L + L_KT + t * LD + ch * 2) = (bf16)f2bf(Kt); *(LAS bf16*)(L + L_RT + t * LD + ch * 2) = (bf16)f2bf(Rt);
;             if (tt & 1) { patt[tt >> 1] = pk2(hAt, At); pvt[tt >> 1] = pk2(vv[tt - 1], vv[tt]); pbh[tt >> 1] = pk2(hBh, Bh); pkh[tt >> 1] = pk2(hKh, Kh); }
;             hAt = At; hBh = Bh; hKh = Kh;
;         }
.LBB0_1418:
	v_cndmask_b32_e64 v182, v185, 0, s[82:83]
	v_readlane_b32 s66, v254, 40
	v_add_f32_e32 v47, v47, v182
	v_readlane_b32 s67, v254, 41
	s_or_b64 vcc, s[40:41], s[50:51]
	s_mov_b32 s17, s16
	v_cndmask_b32_e64 v47, v182, v47, s[66:67]
	v_readlane_b32 s66, v254, 42
	v_add_f32_e32 v102, v102, v47
	v_readlane_b32 s67, v254, 43
	s_nop 1
	v_cndmask_b32_e64 v47, v47, v102, s[66:67]
	v_readlane_b32 s66, v254, 44
	v_add_f32_e32 v102, v103, v47
	v_readlane_b32 s67, v254, 45
	s_nop 1
	v_cndmask_b32_e64 v47, v47, v102, s[66:67]
	v_readlane_b32 s66, v254, 46
	v_add_f32_e32 v98, v98, v47
	v_readlane_b32 s67, v254, 47
	s_nop 1
	v_cndmask_b32_e64 v47, v47, v98, s[66:67]
	v_readlane_b32 s66, v254, 48
	v_add_f32_e32 v98, v99, v47
	v_readlane_b32 s67, v254, 49
	v_max_f32_e64 v99, s77, s77
	v_max_f32_e32 v99, 0x179abe15, v99
	v_cndmask_b32_e64 v47, v47, v98, s[66:67]
	v_readlane_b32 s66, v254, 50
	v_max_f32_e64 v98, s71, s71
	v_add_f32_e32 v96, v96, v47
	v_readlane_b32 s67, v254, 51
	v_max_f32_e32 v98, 0x179abe15, v98
	v_rsq_f32_e32 v98, v98
	v_cndmask_b32_e64 v47, v47, v96, s[66:67]
	v_rsq_f32_e32 v99, v99
	v_add_f32_e32 v102, v97, v47
	v_max_f32_e64 v97, s14, s14
	v_readlane_b32 s14, v254, 53
	v_readlane_b32 s15, v254, 54
	v_pk_mul_f32 v[88:89], v[88:89], v[98:99]
	v_max_f32_e64 v98, s69, s69
	v_cndmask_b32_e64 v47, v47, v102, s[14:15]
	v_max_f32_e64 v99, s70, s70
	v_add_f32_e32 v102, v177, v47
	v_max_f32_e32 v98, 0x179abe15, v98
	v_max_f32_e32 v99, 0x179abe15, v99
	v_mul_f32_e32 v102, 0x3fb8aa3b, v102
	v_max_f32_e64 v96, s93, s93
	v_rsq_f32_e32 v98, v98
	v_rsq_f32_e32 v99, v99
	v_exp_f32_e32 v103, v102
	v_max_f32_e32 v96, 0x179abe15, v96
	v_max_f32_e32 v97, 0x179abe15, v97
	v_rsq_f32_e32 v96, v96
	v_rsq_f32_e32 v97, v97
	v_pk_mul_f32 v[98:99], v[80:81], v[98:99]
	v_rcp_f32_e32 v80, v103
	v_mul_f32_e32 v81, 0x3fb8aa3b, v47
	v_pk_mul_f32 v[96:97], v[100:101], v[96:97]
	v_exp_f32_e32 v102, v81
	v_pk_mul_f32 v[38:39], v[38:39], v[96:97]
	s_mul_i32 s14, s16, 0x480
	v_mul_f32_e32 v81, v38, v80
	v_pk_mul_f32 v[186:187], v[86:87], v[98:99]
	v_mul_f32_e32 v86, v40, v80
	v_mul_f32_e32 v87, v173, v103
	v_cvt_pk_bf16_f32 v81, v81, s0
	v_add_u32_e32 v173, s14, v58
	ds_write_b16 v173, v81 offset:9216
	v_cvt_pk_bf16_f32 v81, v86, s0
	v_add_f32_e32 v86, v176, v47
	v_mul_f32_e32 v86, 0x3fb8aa3b, v86
	v_max_f32_e64 v100, s64, s64
	v_max_f32_e64 v101, s65, s65
	v_exp_f32_e32 v176, v86
	v_max_f32_e32 v100, 0x179abe15, v100
	v_max_f32_e32 v101, 0x179abe15, v101
	v_rsq_f32_e32 v100, v100
	v_rsq_f32_e32 v101, v101
	ds_write_b16 v173, v81 offset:18432
	v_cvt_pk_bf16_f32 v81, v87, s0
	ds_write_b16 v173, v81 offset:27648
	v_rcp_f32_e32 v81, v176
	v_pk_mul_f32 v[44:45], v[44:45], v[100:101]
	v_pk_mul_f32 v[86:87], v[102:103], v[96:97] neg_lo:[0,1] neg_hi:[0,1]
	v_pk_mul_f32 v[100:101], v[94:95], v[44:45]
	v_cvt_pk_bf16_f32 v94, v86, s0
	ds_write_b16 v173, v94
	v_mul_f32_e32 v94, v39, v81
	v_mul_f32_e32 v95, v41, v81
	v_cvt_pk_bf16_f32 v94, v94, s0
	v_mul_f32_e32 v96, v174, v176
	ds_write_b16 v173, v94 offset:9360
	v_cvt_pk_bf16_f32 v94, v95, s0
	ds_write_b16 v173, v94 offset:18576
	v_cvt_pk_bf16_f32 v94, v96, s0
	ds_write_b16 v173, v94 offset:27792
	v_add_f32_e32 v94, v179, v47
	v_mul_f32_e32 v94, 0x3fb8aa3b, v94
	v_exp_f32_e32 v177, v94
	v_pk_mul_f32 v[82:83], v[82:83], v[88:89]
	v_pk_mul_f32 v[80:81], v[46:47], v[80:81] op_sel_hi:[0,1]
	v_pk_mul_f32 v[40:41], v[40:41], v[80:81]
	v_rcp_f32_e32 v96, v177
	v_pk_mul_f32 v[94:95], v[38:39], v[80:81]
	v_cvt_pk_bf16_f32 v80, v36, v37
	v_cvt_pk_bf16_f32 v97, v87, s0
	v_mul_f32_e32 v36, v82, v96
	v_cvt_pk_bf16_f32 v36, v36, s0
	ds_write_b16 v173, v36 offset:9504
	v_add_f32_e32 v36, v181, v47
	v_mul_f32_e32 v36, 0x3fb8aa3b, v36
	v_exp_f32_e32 v36, v36
	ds_write_b16 v173, v97 offset:144
	v_mul_f32_e32 v37, v78, v96
	v_mul_f32_e32 v39, v175, v177
	v_rcp_f32_e32 v97, v36
	v_cvt_pk_bf16_f32 v37, v37, s0
	v_cvt_pk_bf16_f32 v38, v86, v87
	v_cvt_pk_bf16_f32 v86, v94, v95
	v_cvt_pk_bf16_f32 v94, v40, v41
	ds_write_b16 v173, v37 offset:18720
	v_cvt_pk_bf16_f32 v37, v39, s0
	v_pk_mul_f32 v[40:41], v[176:177], v[88:89] neg_lo:[0,1] neg_hi:[0,1]
	ds_write_b16 v173, v37 offset:27936
	v_cvt_pk_bf16_f32 v37, v40, s0
	ds_write_b16 v173, v37 offset:288
	v_mul_f32_e32 v37, v83, v97
	v_mul_f32_e32 v39, v79, v97
	v_cvt_pk_bf16_f32 v37, v37, s0
	v_mul_f32_e32 v81, v178, v36
	ds_write_b16 v173, v37 offset:9648
	v_cvt_pk_bf16_f32 v37, v39, s0
	ds_write_b16 v173, v37 offset:18864
	v_cvt_pk_bf16_f32 v37, v81, s0
	ds_write_b16 v173, v37 offset:28080
	v_add_f32_e32 v37, v184, v47
	v_mul_f32_e32 v37, 0x3fb8aa3b, v37
	v_exp_f32_e32 v37, v37
	v_cvt_pk_bf16_f32 v39, v40, v41
	v_cvt_pk_bf16_f32 v87, v41, s0
	v_cvt_pk_bf16_f32 v81, v76, v77
	v_rcp_f32_e32 v40, v37
	v_mul_f32_e32 v77, v180, v37
	v_pk_mul_f32 v[36:37], v[36:37], v[98:99] neg_lo:[0,1] neg_hi:[0,1]
	v_pk_mul_f32 v[88:89], v[46:47], v[96:97] op_sel_hi:[0,1]
	v_mul_f32_e32 v41, v186, v40
	v_mul_f32_e32 v76, v90, v40
	v_cvt_pk_bf16_f32 v41, v41, s0
	ds_write_b16 v173, v41 offset:9792
	v_cvt_pk_bf16_f32 v41, v76, s0
	v_add_f32_e32 v76, v190, v47
	v_mul_f32_e32 v76, 0x3fb8aa3b, v76
	v_exp_f32_e32 v76, v76
	ds_write_b16 v173, v41 offset:19008
	v_cvt_pk_bf16_f32 v41, v77, s0
	ds_write_b16 v173, v41 offset:28224
	v_rcp_f32_e32 v41, v76
	v_cvt_pk_bf16_f32 v77, v36, s0
	v_pk_mul_f32 v[78:79], v[78:79], v[88:89]
	ds_write_b16 v173, v77 offset:576
	v_mul_f32_e32 v77, v187, v41
	v_cvt_pk_bf16_f32 v95, v78, v79
	v_mul_f32_e32 v78, v91, v41
	v_cvt_pk_bf16_f32 v77, v77, s0
	v_mul_f32_e32 v79, v183, v76
	ds_write_b16 v173, v77 offset:9936
	v_cvt_pk_bf16_f32 v77, v78, s0
	ds_write_b16 v173, v77 offset:19152
; __device__ __forceinline__ void rwkv_chunk_group(Frame& F, int bc, unsigned long long& tsub) {
;     ...
;         for (int tt = 0; tt < 8; ++tt) { const int t = tb + tt; const float cl = offs + ld[tt];
;             const float e_in = __expf(cl), e_inv = __builtin_amdgcn_rcpf(e_in), e_hat = etot * e_inv;
;             const float At = aa[tt] * e_ex, Bt = bb[tt] * e_inv, Kt = kp[tt] * e_inv, Rt = rr[tt] * e_in, Bh = bb[tt] * e_hat, Kh = kp[tt] * e_hat; e_ex = e_in;
;             *(LAS bf16*)(L + L_AT + t * LD + ch * 2) = (bf16)f2bf(At); *(LAS bf16*)(L + L_BT + t * LD + ch * 2) = (bf16)f2bf(Bt);
;             *(LAS bf16*)(L + L_KT + t * LD + ch * 2) = (bf16)f2bf(Kt); *(LAS bf16*)(L + L_RT + t * LD + ch * 2) = (bf16)f2bf(Rt);
;             if (tt & 1) { patt[tt >> 1] = pk2(hAt, At); pvt[tt >> 1] = pk2(vv[tt - 1], vv[tt]); pbh[tt >> 1] = pk2(hBh, Bh); pkh[tt >> 1] = pk2(hKh, Kh); }
;             hAt = At; hBh = Bh; hKh = Kh;
;         }
;         *(LAS v4u*)(L + L_ATT + ch * LD + tb * 2) = (v4u){patt[0], patt[1], patt[2], patt[3]};
;         *(LAS v4u*)(L + L_VT + ch * LD + tb * 2) = (v4u){pvt[0], pvt[1], pvt[2], pvt[3]};
;         *(LAS v4u*)(L + L_BH + ch * LD + tb * 2) = (v4u){pbh[0], pbh[1], pbh[2], pbh[3]};
;         *(LAS v4u*)(L + L_KH + ch * LD + tb * 2) = (v4u){pkh[0], pkh[1], pkh[2], pkh[3]};
;         LBAR();
;     }
;     TSUB(2);
; #pragma unroll
;     for (int q = 0; q < 2; ++q) { const int tw = 2 * w + q, p0 = 16 * (tw >> 2), q0 = 16 * (tw & 3);
;         f32x4 m = mm_tile(L + L_AT, LD, q0, L + L_BT, LD, p0, 2, Z4, fr, fq);
;         f32x4 nak = mm_tile(L + L_KT, LD, q0, L + L_AT, LD, p0, 2, Z4, fr, fq);
;         f32x4 nrk = mm_tile(L + L_KT, LD, q0, L + L_RT, LD, p0, 2, Z4, fr, fq);
;         f32x4 nrb = mm_tile(L + L_BT, LD, q0, L + L_RT, LD, p0, 2, Z4, fr, fq);
;         f32x4 tt;
;         const int p = p0 + fr;
; #pragma unroll
;         for (int v = 0; v < 4; ++v) { const int qq = q0 + 4 * fq + v;
;             if (!(p < qq)) m[v] = 0.f;
;             if (!(qq < p)) nak[v] = 0.f;
;             if (!(qq <= p)) { nrk[v] = 0.f; nrb[v] = 0.f; }
;             tt[v] = (p == qq) ? 1.f : 0.f; }
;         const int o = p * LD + (q0 + 4 * fq) * 2;
;         st4_lds(L + L_M + o, m); st4t_lds(L + L_MT, p, q0 + 4 * fq, m); st4_lds(L + L_NAK + o, nak); st4_lds(L + L_NRK + o, nrk); st4_lds(L + L_NRB + o, nrb); st4_lds(L + L_TT + o, tt);
	v_cvt_pk_bf16_f32 v77, v79, s0
	ds_write_b16 v173, v77 offset:28368
	v_add_f32_e32 v77, v192, v47
	v_mul_f32_e32 v77, 0x3fb8aa3b, v77
	v_exp_f32_e32 v77, v77
	v_pk_mul_f32 v[40:41], v[46:47], v[40:41] op_sel_hi:[0,1]
	v_pk_mul_f32 v[82:83], v[82:83], v[88:89]
	v_pk_mul_f32 v[78:79], v[90:91], v[40:41]
	v_pk_mul_f32 v[88:89], v[186:187], v[40:41]
	v_cvt_pk_bf16_f32 v40, v36, v37
	v_rcp_f32_e32 v36, v77
	ds_write_b16 v173, v87 offset:432
	v_cvt_pk_bf16_f32 v87, v82, v83
	v_cvt_pk_bf16_f32 v82, v37, s0
	v_mul_f32_e32 v37, v100, v36
	v_mul_f32_e32 v41, v42, v36
	v_cvt_pk_bf16_f32 v37, v37, s0
	ds_write_b16 v173, v37 offset:10080
	v_cvt_pk_bf16_f32 v37, v41, s0
	v_add_f32_e32 v41, v52, v47
	v_mul_f32_e32 v41, 0x3fb8aa3b, v41
	v_exp_f32_e32 v41, v41
	v_cvt_pk_bf16_f32 v96, v78, v79
	v_mul_f32_e32 v78, v188, v77
	ds_write_b16 v173, v37 offset:19296
	v_cvt_pk_bf16_f32 v37, v78, s0
	ds_write_b16 v173, v37 offset:28512
	v_rcp_f32_e32 v37, v41
	v_pk_mul_f32 v[44:45], v[76:77], v[44:45] neg_lo:[0,1] neg_hi:[0,1]
	v_mul_f32_e32 v41, v191, v41
	v_cvt_pk_bf16_f32 v47, v44, s0
	ds_write_b16 v173, v47 offset:864
	v_mul_f32_e32 v47, v101, v37
	v_mul_f32_e32 v52, v43, v37
	v_cvt_pk_bf16_f32 v47, v47, s0
	ds_write_b16 v173, v47 offset:10224
	v_cvt_pk_bf16_f32 v47, v52, s0
	v_cvt_pk_bf16_f32 v41, v41, s0
	v_pk_mul_f32 v[36:37], v[46:47], v[36:37] op_sel_hi:[0,1]
	v_cvt_pk_bf16_f32 v76, v45, s0
	ds_write_b16 v173, v41 offset:28656
	v_pk_mul_f32 v[42:43], v[42:43], v[36:37]
	v_pk_mul_f32 v[36:37], v[100:101], v[36:37]
	v_cvt_pk_bf16_f32 v41, v44, v45
	ds_write_b16 v173, v82 offset:720
	v_cvt_pk_bf16_f32 v82, v84, v85
	v_cvt_pk_bf16_f32 v88, v88, v89
	ds_write_b16 v173, v76 offset:1008
	ds_write_b16 v173, v47 offset:19440
	v_cvt_pk_bf16_f32 v97, v42, v43
	v_cvt_pk_bf16_f32 v89, v36, v37
	v_cvt_pk_bf16_f32 v83, v92, v93
	ds_write_b128 v141, v[38:41] offset:36864
	ds_write_b128 v141, v[80:83] offset:46080
	ds_write_b128 v141, v[86:89] offset:55296
	ds_write_b128 v141, v[94:97] offset:64512
	s_waitcnt lgkmcnt(0)
	s_barrier
	v_add_u32_e32 v76, v106, v110
	ds_read_b128 v[36:39], v76
	ds_read_b128 v[40:43], v76 offset:64
	ds_read_b128 v[44:47], v107 offset:9216
	ds_read_b128 v[78:81], v107 offset:9280
	s_waitcnt lgkmcnt(1)
	v_mfma_f32_16x16x32_bf16 v[36:39], v[36:39], v[44:47], 0
	ds_read_b128 v[44:47], v76 offset:18432
	v_mov_b32_e32 v52, s95
	s_waitcnt lgkmcnt(1)
	v_mfma_f32_16x16x32_bf16 v[36:39], v[40:43], v[78:81], v[36:39]
	ds_read_b128 v[40:43], v76 offset:18496
	ds_read_b128 v[78:81], v107
	ds_read_b128 v[82:85], v107 offset:64
	s_waitcnt lgkmcnt(1)
	v_mfma_f32_16x16x32_bf16 v[78:81], v[44:47], v[78:81], 0
	s_nop 2
	v_cndmask_b32_e64 v77, v52, v36, s[48:49]
	v_mov_b32_e32 v36, s95
	v_cndmask_b32_e64 v37, v37, 0, s[50:51]
	s_waitcnt lgkmcnt(0)
	v_mfma_f32_16x16x32_bf16 v[78:81], v[40:43], v[82:85], v[78:81]
	ds_read_b128 v[82:85], v107 offset:27648
	ds_read_b128 v[86:89], v107 offset:27712
	ds_read_b128 v[90:93], v76 offset:9216
	v_cndmask_b32_e64 v38, 0, v38, s[52:53]
	s_waitcnt lgkmcnt(2)
	v_mfma_f32_16x16x32_bf16 v[44:47], v[44:47], v[82:85], 0
	v_cndmask_b32_e64 v39, 0, v39, s[54:55]
	s_nop 0
	v_cndmask_b32_e64 v80, 0, v80, s[38:39]
	v_cndmask_b32_e64 v79, 0, v79, s[40:41]
	s_waitcnt lgkmcnt(1)
	v_mfma_f32_16x16x32_bf16 v[40:43], v[40:43], v[86:89], v[44:47]
	v_cndmask_b32_e32 v78, 0, v78, vcc
	s_or_b64 vcc, s[46:47], s[58:59]
	s_nop 0
	ds_read_b128 v[44:47], v76 offset:9280
	s_waitcnt lgkmcnt(1)
	v_mfma_f32_16x16x32_bf16 v[82:85], v[90:93], v[82:85], 0
	s_nop 1
	v_cndmask_b32_e64 v36, v40, v36, s[48:49]
	v_cndmask_b32_e64 v40, v36, v40, s[50:51]
	v_cvt_pk_bf16_f32 v36, v77, v37
	s_waitcnt lgkmcnt(0)
	v_mfma_f32_16x16x32_bf16 v[44:47], v[44:47], v[86:89], v[82:85]
	v_cvt_pk_bf16_f32 v37, v38, v39
	v_add_u32_e32 v38, s33, v127
	v_cndmask_b32_e64 v41, 0, v41, s[50:51]
	s_nop 4
	v_cndmask_b32_e64 v52, v44, v52, s[48:49]
	v_cndmask_b32_e64 v44, v52, v44, s[50:51]
	v_cndmask_b32_e64 v52, 0, v81, s[36:37]
	v_cndmask_b32_e64 v42, v42, 0, s[52:53]
	v_cndmask_b32_e64 v43, v43, 0, s[54:55]
	ds_write_b64 v38, v[36:37]
	ds_write_b16 v148, v36
	ds_write_b16_d16_hi v148, v36 offset:144
	ds_write_b16 v148, v37 offset:288
	ds_write_b16_d16_hi v148, v37 offset:432
	v_cvt_pk_bf16_f32 v36, v78, v79
	v_cvt_pk_bf16_f32 v37, v80, v52
	v_add_u32_e32 v38, s2, v127
	v_cndmask_b32_e64 v45, 0, v45, s[50:51]
	v_cndmask_b32_e64 v46, v46, 0, s[52:53]
	v_cndmask_b32_e64 v47, v47, 0, s[54:55]
	ds_write_b64 v38, v[36:37]
	v_cvt_pk_bf16_f32 v36, v40, v41
	v_cvt_pk_bf16_f32 v37, v42, v43
	v_add_u32_e32 v38, s0, v127
	ds_write_b64 v38, v[36:37]
	v_cvt_pk_bf16_f32 v36, v44, v45
	v_cvt_pk_bf16_f32 v37, v46, v47
	v_add_u32_e32 v38, s3, v127
	ds_write_b64 v38, v[36:37]
	v_add_u32_e32 v36, s74, v127
	ds_write_b64 v36, v[60:61]
	v_add_u32_e32 v77, v106, v128
	ds_read_b128 v[36:39], v77
	ds_read_b128 v[40:43], v77 offset:64
	ds_read_b128 v[44:47], v107 offset:9216
	ds_read_b128 v[78:81], v107 offset:9280
	s_waitcnt lgkmcnt(1)
	v_mfma_f32_16x16x32_bf16 v[36:39], v[36:39], v[44:47], 0
	ds_read_b128 v[44:47], v77 offset:18432
	v_mov_b32_e32 v52, s95
	s_waitcnt lgkmcnt(1)
	v_mfma_f32_16x16x32_bf16 v[36:39], v[40:43], v[78:81], v[36:39]
	ds_read_b128 v[40:43], v77 offset:18496
	ds_read_b128 v[78:81], v107
	ds_read_b128 v[82:85], v107 offset:64
	s_waitcnt lgkmcnt(1)
	v_mfma_f32_16x16x32_bf16 v[78:81], v[44:47], v[78:81], 0
	s_nop 2
	v_cndmask_b32_e64 v37, v37, 0, s[58:59]
	v_cndmask_b32_e64 v38, 0, v38, s[60:61]
	v_cndmask_b32_e64 v39, 0, v39, s[62:63]
	s_waitcnt lgkmcnt(0)
	v_mfma_f32_16x16x32_bf16 v[78:81], v[40:43], v[82:85], v[78:81]
	ds_read_b128 v[82:85], v107 offset:27648
	ds_read_b128 v[86:89], v107 offset:27712
	ds_read_b128 v[90:93], v77 offset:9216
	s_waitcnt lgkmcnt(2)
; __device__ __forceinline__ void st4_lds(LAS unsigned char* p, f32x4 v) { v2u w; w.x = pk2(v[0], v[1]); w.y = pk2(v[2], v[3]); *(LAS v2u*)p = w; }
; __device__ __forceinline__ f32x4 ld4_lds(const LAS unsigned char* p) { const v2u w = *(const LAS v2u*)p; return (f32x4){bflo(w.x), bfhi(w.x), bflo(w.y), bfhi(w.y)}; }
; #define LBAR() asm volatile("s_waitcnt lgkmcnt(0)\n\ts_barrier" ::: "memory")
; #define TSUB(k) do { } while (0)
; __device__ __forceinline__ void rwkv_chunk_group(Frame& F, int bc, unsigned long long& tsub) {
;     ...
;         for (int v = 0; v < 4; ++v) { const int qq = q0 + 4 * fq + v;
;             if (!(p < qq)) m[v] = 0.f;
;             if (!(qq < p)) nak[v] = 0.f;
;             if (!(qq <= p)) { nrk[v] = 0.f; nrb[v] = 0.f; }
;             tt[v] = (p == qq) ? 1.f : 0.f; }
;         const int o = p * LD + (q0 + 4 * fq) * 2;
;         st4_lds(L + L_M + o, m); st4t_lds(L + L_MT, p, q0 + 4 * fq, m); st4_lds(L + L_NAK + o, nak); st4_lds(L + L_NRK + o, nrk); st4_lds(L + L_NRB + o, nrb); st4_lds(L + L_TT + o, tt);
;     }
;     LBAR();
;     TSUB(3);
;     for (int it = 0; it < 6; ++it) {
;         const int rM = (it & 1) ? L_AT : L_M, rMT = (it & 1) ? L_BT : L_MT, rTT = (it & 1) ? L_KT : L_TT;
;         const int wM = (it & 1) ? L_M : L_AT, wMT = (it & 1) ? L_MT : L_BT, wTT = (it & 1) ? L_TT : L_KT;
; #pragma unroll
;         for (int q = 0; q < 2; ++q) { const int tw = 2 * w + q, p0 = 16 * (tw >> 2), q0 = 16 * (tw & 3); const int o = (p0 + fr) * LD + (q0 + 4 * fq) * 2;
;             f32x4 tn = Z4, mn = Z4;
;             if (q0 <= p0) { tn = mm_tile(L + rM, LD, q0, L + rTT, LD, p0, 2, ld4_lds(L + rTT + o), fr, fq);
;                           }
;             if (q0 >= p0 && it < 5) mn = mm_tile(L + rMT, LD, q0, L + rM, LD, p0, 2, Z4, fr, fq);
;             st4_lds(L + wTT + o, tn); if (it < 5) { st4_lds(L + wM + o, mn); st4t_lds(L + wMT, p0 + fr, q0 + 4 * fq, mn); } }
;         LBAR();
;     }
	v_mfma_f32_16x16x32_bf16 v[44:47], v[44:47], v[82:85], 0
	s_nop 2
	v_cndmask_b32_e64 v80, 0, v80, s[44:45]
	v_cndmask_b32_e64 v79, 0, v79, s[46:47]
	v_cndmask_b32_e32 v78, 0, v78, vcc
	s_waitcnt lgkmcnt(1)
	v_mfma_f32_16x16x32_bf16 v[40:43], v[40:43], v[86:89], v[44:47]
	s_andn2_b64 vcc, exec, s[78:79]
	s_nop 1
	ds_read_b128 v[44:47], v77 offset:9280
	s_waitcnt lgkmcnt(1)
	v_mfma_f32_16x16x32_bf16 v[82:85], v[90:93], v[82:85], 0
	s_nop 1
	v_cndmask_b32_e64 v41, 0, v41, s[58:59]
	v_cndmask_b32_e64 v42, v42, 0, s[60:61]
	v_cndmask_b32_e64 v43, v43, 0, s[62:63]
	s_waitcnt lgkmcnt(0)
	v_mfma_f32_16x16x32_bf16 v[44:47], v[44:47], v[86:89], v[82:85]
	s_nop 2
	v_cndmask_b32_e64 v82, v52, v36, s[56:57]
	v_mov_b32_e32 v36, s95
	v_cndmask_b32_e64 v36, v40, v36, s[56:57]
	s_nop 1
	v_cndmask_b32_e64 v52, v44, v52, s[56:57]
	v_cndmask_b32_e64 v44, v52, v44, s[58:59]
	v_cndmask_b32_e64 v40, v36, v40, s[58:59]
	v_cndmask_b32_e64 v52, 0, v81, s[42:43]
	v_cvt_pk_bf16_f32 v36, v82, v37
	v_cvt_pk_bf16_f32 v37, v38, v39
	v_add_u32_e32 v38, s33, v129
	ds_write_b64 v38, v[36:37]
	ds_write_b16 v149, v36
	ds_write_b16_d16_hi v149, v36 offset:144
	ds_write_b16 v149, v37 offset:288
	ds_write_b16_d16_hi v149, v37 offset:432
	v_cvt_pk_bf16_f32 v36, v78, v79
	v_cvt_pk_bf16_f32 v37, v80, v52
	v_add_u32_e32 v38, s2, v129
	v_cndmask_b32_e64 v45, 0, v45, s[58:59]
	v_cndmask_b32_e64 v46, v46, 0, s[60:61]
	v_cndmask_b32_e64 v47, v47, 0, s[62:63]
	ds_write_b64 v38, v[36:37]
	v_cvt_pk_bf16_f32 v36, v40, v41
	v_cvt_pk_bf16_f32 v37, v42, v43
	v_add_u32_e32 v38, s0, v129
	ds_write_b64 v38, v[36:37]
	v_cvt_pk_bf16_f32 v36, v44, v45
	v_cvt_pk_bf16_f32 v37, v46, v47
	v_add_u32_e32 v38, s3, v129
	ds_write_b64 v38, v[36:37]
	v_add_u32_e32 v36, s74, v129
	ds_write_b64 v36, v[72:73]
	s_waitcnt lgkmcnt(0)
	s_barrier
	v_mov_b32_e32 v78, v127
	v_mov_b32_e32 v79, v129
	v_add_u32_e32 v173, v106, v110
	v_add_u32_e32 v174, v106, v128
	v_add_u32_e32 v97, 0x12000, v127
	v_add_u32_e32 v98, 0x12000, v129
	v_mov_b32_e32 v102, 0
	v_mov_b32_e32 v103, 0
	v_add_u32_e32 v175, 0x12000, v173
	v_add_u32_e32 v96, 0x12000, v174
	s_and_b64 vcc, exec, s[78:79]
	s_cbranch_vccz .La2_FTFT
	s_and_b64 vcc, exec, s[84:85]
	s_cbranch_vccz .La2_TFTx
	ds_read_b64 v[242:243], v97 offset:18432
	ds_read_b128 v[176:179], v175 offset:0
	ds_read_b128 v[224:227], v132 offset:18432
	ds_read_b128 v[184:187], v175 offset:9216
	ds_read_b128 v[232:235], v132 offset:0
	ds_read_b128 v[192:195], v96 offset:9216
	ds_read_b128 v[180:183], v175 offset:64
	ds_read_b128 v[228:231], v132 offset:18496
	ds_read_b128 v[188:191], v175 offset:9280
	ds_read_b128 v[236:239], v132 offset:64
	ds_read_b128 v[196:199], v96 offset:9280
	s_waitcnt lgkmcnt(10)
	v_lshlrev_b32_e32 v240, 16, v242
	v_and_b32_e32 v241, 0xffff0000, v242
	v_lshlrev_b32_e32 v242, 16, v243
	v_and_b32_e32 v243, 0xffff0000, v243
	s_nop 1
	s_waitcnt lgkmcnt(8)
	v_mfma_f32_16x16x32_bf16 v[240:243], v[176:179], v[224:227], v[240:243]
	s_waitcnt lgkmcnt(6)
	v_mfma_f32_16x16x32_bf16 v[244:247], v[184:187], v[232:235], 0
	s_waitcnt lgkmcnt(5)
	v_mfma_f32_16x16x32_bf16 v[248:251], v[192:195], v[232:235], 0
	s_waitcnt lgkmcnt(3)
	v_mfma_f32_16x16x32_bf16 v[240:243], v[180:183], v[228:231], v[240:243]
	s_waitcnt lgkmcnt(1)
	v_mfma_f32_16x16x32_bf16 v[244:247], v[188:191], v[236:239], v[244:247]
	s_waitcnt lgkmcnt(0)
	v_mfma_f32_16x16x32_bf16 v[248:251], v[196:199], v[236:239], v[248:251]
	s_nop 7
	v_cvt_pk_bf16_f32 v176, v240, v241
	v_cvt_pk_bf16_f32 v177, v242, v243
	v_cvt_pk_bf16_f32 v184, v244, v245
	v_cvt_pk_bf16_f32 v185, v246, v247
	v_cvt_pk_bf16_f32 v192, v248, v249
	v_cvt_pk_bf16_f32 v193, v250, v251
	ds_write_b64 v127, v[176:177] offset:18432
	ds_write_b64 v127, v[184:185] offset:0
	ds_write_b16 v151, v184 offset:9216
	ds_write_b16_d16_hi v151, v184 offset:9360
	ds_write_b16 v151, v185 offset:9504
	ds_write_b16_d16_hi v151, v185 offset:9648
	ds_write_b64 v129, v[102:103] offset:18432
	ds_write_b64 v129, v[192:193] offset:0
	ds_write_b16 v152, v192 offset:9216
	ds_write_b16_d16_hi v152, v192 offset:9360
	ds_write_b16 v152, v193 offset:9504
	ds_write_b16_d16_hi v152, v193 offset:9648
	s_waitcnt lgkmcnt(0)
	s_barrier
	ds_read_b64 v[242:243], v127 offset:18432
	ds_read_b128 v[176:179], v173 offset:0
	ds_read_b128 v[224:227], v107 offset:18432
	ds_read_b128 v[184:187], v173 offset:9216
	ds_read_b128 v[232:235], v107 offset:0
	ds_read_b128 v[192:195], v174 offset:9216
	ds_read_b128 v[180:183], v173 offset:64
	ds_read_b128 v[228:231], v107 offset:18496
	ds_read_b128 v[188:191], v173 offset:9280
	ds_read_b128 v[236:239], v107 offset:64
	ds_read_b128 v[196:199], v174 offset:9280
	s_waitcnt lgkmcnt(10)
	v_lshlrev_b32_e32 v240, 16, v242
	v_and_b32_e32 v241, 0xffff0000, v242
	v_lshlrev_b32_e32 v242, 16, v243
	v_and_b32_e32 v243, 0xffff0000, v243
	s_nop 1
	s_waitcnt lgkmcnt(8)
	v_mfma_f32_16x16x32_bf16 v[240:243], v[176:179], v[224:227], v[240:243]
	s_waitcnt lgkmcnt(6)
	v_mfma_f32_16x16x32_bf16 v[244:247], v[184:187], v[232:235], 0
	s_waitcnt lgkmcnt(5)
	v_mfma_f32_16x16x32_bf16 v[248:251], v[192:195], v[232:235], 0
	s_waitcnt lgkmcnt(3)
	v_mfma_f32_16x16x32_bf16 v[240:243], v[180:183], v[228:231], v[240:243]
	s_waitcnt lgkmcnt(1)
	v_mfma_f32_16x16x32_bf16 v[244:247], v[188:191], v[236:239], v[244:247]
	s_waitcnt lgkmcnt(0)
	v_mfma_f32_16x16x32_bf16 v[248:251], v[196:199], v[236:239], v[248:251]
	s_nop 7
	v_cvt_pk_bf16_f32 v176, v240, v241
	v_cvt_pk_bf16_f32 v177, v242, v243
	v_cvt_pk_bf16_f32 v184, v244, v245
	v_cvt_pk_bf16_f32 v185, v246, v247
	v_cvt_pk_bf16_f32 v192, v248, v249
	v_cvt_pk_bf16_f32 v193, v250, v251
	ds_write_b64 v97, v[176:177] offset:18432
	ds_write_b64 v97, v[184:185] offset:0
	ds_write_b16 v148, v184 offset:0
	ds_write_b16_d16_hi v148, v184 offset:144
	ds_write_b16 v148, v185 offset:288
	ds_write_b16_d16_hi v148, v185 offset:432
	ds_write_b64 v98, v[102:103] offset:18432
	ds_write_b64 v98, v[192:193] offset:0
	ds_write_b16 v149, v192 offset:0
	ds_write_b16_d16_hi v149, v192 offset:144
	ds_write_b16 v149, v193 offset:288
	ds_write_b16_d16_hi v149, v193 offset:432
	s_waitcnt lgkmcnt(0)
	s_barrier
; __device__ __forceinline__ void st4_lds(LAS unsigned char* p, f32x4 v) { v2u w; w.x = pk2(v[0], v[1]); w.y = pk2(v[2], v[3]); *(LAS v2u*)p = w; }
; __device__ __forceinline__ f32x4 ld4_lds(const LAS unsigned char* p) { const v2u w = *(const LAS v2u*)p; return (f32x4){bflo(w.x), bfhi(w.x), bflo(w.y), bfhi(w.y)}; }
; #define LBAR() asm volatile("s_waitcnt lgkmcnt(0)\n\ts_barrier" ::: "memory")
; __device__ __forceinline__ void rwkv_chunk_group(Frame& F, int bc, unsigned long long& tsub) {
;     ...
;     for (int it = 0; it < 6; ++it) {
;         const int rM = (it & 1) ? L_AT : L_M, rMT = (it & 1) ? L_BT : L_MT, rTT = (it & 1) ? L_KT : L_TT;
;         const int wM = (it & 1) ? L_M : L_AT, wMT = (it & 1) ? L_MT : L_BT, wTT = (it & 1) ? L_TT : L_KT;
; #pragma unroll
;         for (int q = 0; q < 2; ++q) { const int tw = 2 * w + q, p0 = 16 * (tw >> 2), q0 = 16 * (tw & 3); const int o = (p0 + fr) * LD + (q0 + 4 * fq) * 2;
;             f32x4 tn = Z4, mn = Z4;
;             if (q0 <= p0) { tn = mm_tile(L + rM, LD, q0, L + rTT, LD, p0, 2, ld4_lds(L + rTT + o), fr, fq);
;                           }
;             if (q0 >= p0 && it < 5) mn = mm_tile(L + rMT, LD, q0, L + rM, LD, p0, 2, Z4, fr, fq);
;             st4_lds(L + wTT + o, tn); if (it < 5) { st4_lds(L + wM + o, mn); st4t_lds(L + wMT, p0 + fr, q0 + 4 * fq, mn); } }
;         LBAR();
;     }
	ds_read_b64 v[242:243], v97 offset:18432
	ds_read_b128 v[176:179], v175 offset:0
	ds_read_b128 v[224:227], v132 offset:18432
	ds_read_b128 v[184:187], v175 offset:9216
	ds_read_b128 v[232:235], v132 offset:0
	ds_read_b128 v[192:195], v96 offset:9216
	ds_read_b128 v[180:183], v175 offset:64
	ds_read_b128 v[228:231], v132 offset:18496
	ds_read_b128 v[188:191], v175 offset:9280
	ds_read_b128 v[236:239], v132 offset:64
	ds_read_b128 v[196:199], v96 offset:9280
	s_waitcnt lgkmcnt(10)
	v_lshlrev_b32_e32 v240, 16, v242
	v_and_b32_e32 v241, 0xffff0000, v242
	v_lshlrev_b32_e32 v242, 16, v243
	v_and_b32_e32 v243, 0xffff0000, v243
	s_nop 1
	s_waitcnt lgkmcnt(8)
	v_mfma_f32_16x16x32_bf16 v[240:243], v[176:179], v[224:227], v[240:243]
	s_waitcnt lgkmcnt(6)
	v_mfma_f32_16x16x32_bf16 v[244:247], v[184:187], v[232:235], 0
	s_waitcnt lgkmcnt(5)
	v_mfma_f32_16x16x32_bf16 v[248:251], v[192:195], v[232:235], 0
	s_waitcnt lgkmcnt(3)
	v_mfma_f32_16x16x32_bf16 v[240:243], v[180:183], v[228:231], v[240:243]
	s_waitcnt lgkmcnt(1)
	v_mfma_f32_16x16x32_bf16 v[244:247], v[188:191], v[236:239], v[244:247]
	s_waitcnt lgkmcnt(0)
	v_mfma_f32_16x16x32_bf16 v[248:251], v[196:199], v[236:239], v[248:251]
	s_nop 7
	v_cvt_pk_bf16_f32 v176, v240, v241
	v_cvt_pk_bf16_f32 v177, v242, v243
	v_cvt_pk_bf16_f32 v184, v244, v245
	v_cvt_pk_bf16_f32 v185, v246, v247
	v_cvt_pk_bf16_f32 v192, v248, v249
	v_cvt_pk_bf16_f32 v193, v250, v251
	ds_write_b64 v127, v[176:177] offset:18432
	ds_write_b64 v127, v[184:185] offset:0
	ds_write_b16 v151, v184 offset:9216
	ds_write_b16_d16_hi v151, v184 offset:9360
	ds_write_b16 v151, v185 offset:9504
	ds_write_b16_d16_hi v151, v185 offset:9648
	ds_write_b64 v129, v[102:103] offset:18432
	ds_write_b64 v129, v[192:193] offset:0
	ds_write_b16 v152, v192 offset:9216
	ds_write_b16_d16_hi v152, v192 offset:9360
	ds_write_b16 v152, v193 offset:9504
	ds_write_b16_d16_hi v152, v193 offset:9648
	s_waitcnt lgkmcnt(0)
	s_barrier
	ds_read_b64 v[242:243], v127 offset:18432
	ds_read_b128 v[176:179], v173 offset:0
	ds_read_b128 v[224:227], v107 offset:18432
	ds_read_b128 v[184:187], v173 offset:9216
	ds_read_b128 v[232:235], v107 offset:0
	ds_read_b128 v[192:195], v174 offset:9216
	ds_read_b128 v[180:183], v173 offset:64
	ds_read_b128 v[228:231], v107 offset:18496
	ds_read_b128 v[188:191], v173 offset:9280
	ds_read_b128 v[236:239], v107 offset:64
	ds_read_b128 v[196:199], v174 offset:9280
	s_waitcnt lgkmcnt(10)
	v_lshlrev_b32_e32 v240, 16, v242
	v_and_b32_e32 v241, 0xffff0000, v242
	v_lshlrev_b32_e32 v242, 16, v243
	v_and_b32_e32 v243, 0xffff0000, v243
	s_nop 1
	s_waitcnt lgkmcnt(8)
	v_mfma_f32_16x16x32_bf16 v[240:243], v[176:179], v[224:227], v[240:243]
	s_waitcnt lgkmcnt(6)
	v_mfma_f32_16x16x32_bf16 v[244:247], v[184:187], v[232:235], 0
	s_waitcnt lgkmcnt(5)
	v_mfma_f32_16x16x32_bf16 v[248:251], v[192:195], v[232:235], 0
	s_waitcnt lgkmcnt(3)
	v_mfma_f32_16x16x32_bf16 v[240:243], v[180:183], v[228:231], v[240:243]
	s_waitcnt lgkmcnt(1)
	v_mfma_f32_16x16x32_bf16 v[244:247], v[188:191], v[236:239], v[244:247]
	s_waitcnt lgkmcnt(0)
	v_mfma_f32_16x16x32_bf16 v[248:251], v[196:199], v[236:239], v[248:251]
	s_nop 7
	v_cvt_pk_bf16_f32 v176, v240, v241
	v_cvt_pk_bf16_f32 v177, v242, v243
	v_cvt_pk_bf16_f32 v184, v244, v245
	v_cvt_pk_bf16_f32 v185, v246, v247
	v_cvt_pk_bf16_f32 v192, v248, v249
	v_cvt_pk_bf16_f32 v193, v250, v251
	ds_write_b64 v97, v[176:177] offset:18432
	ds_write_b64 v97, v[184:185] offset:0
	ds_write_b16 v148, v184 offset:0
	ds_write_b16_d16_hi v148, v184 offset:144
	ds_write_b16 v148, v185 offset:288
	ds_write_b16_d16_hi v148, v185 offset:432
	ds_write_b64 v98, v[102:103] offset:18432
	ds_write_b64 v98, v[192:193] offset:0
	ds_write_b16 v149, v192 offset:0
	ds_write_b16_d16_hi v149, v192 offset:144
	ds_write_b16 v149, v193 offset:288
	ds_write_b16_d16_hi v149, v193 offset:432
	s_waitcnt lgkmcnt(0)
	s_barrier
	ds_read_b64 v[242:243], v97 offset:18432
	ds_read_b128 v[176:179], v175 offset:0
	ds_read_b128 v[224:227], v132 offset:18432
	ds_read_b128 v[184:187], v175 offset:9216
	ds_read_b128 v[232:235], v132 offset:0
	ds_read_b128 v[192:195], v96 offset:9216
	ds_read_b128 v[180:183], v175 offset:64
	ds_read_b128 v[228:231], v132 offset:18496
	ds_read_b128 v[188:191], v175 offset:9280
	ds_read_b128 v[236:239], v132 offset:64
	ds_read_b128 v[196:199], v96 offset:9280
	s_waitcnt lgkmcnt(10)
	v_lshlrev_b32_e32 v240, 16, v242
	v_and_b32_e32 v241, 0xffff0000, v242
	v_lshlrev_b32_e32 v242, 16, v243
	v_and_b32_e32 v243, 0xffff0000, v243
	s_nop 1
	s_waitcnt lgkmcnt(8)
	v_mfma_f32_16x16x32_bf16 v[240:243], v[176:179], v[224:227], v[240:243]
	s_waitcnt lgkmcnt(6)
	v_mfma_f32_16x16x32_bf16 v[244:247], v[184:187], v[232:235], 0
	s_waitcnt lgkmcnt(5)
	v_mfma_f32_16x16x32_bf16 v[248:251], v[192:195], v[232:235], 0
	s_waitcnt lgkmcnt(3)
	v_mfma_f32_16x16x32_bf16 v[240:243], v[180:183], v[228:231], v[240:243]
	s_waitcnt lgkmcnt(1)
	v_mfma_f32_16x16x32_bf16 v[244:247], v[188:191], v[236:239], v[244:247]
	s_waitcnt lgkmcnt(0)
	v_mfma_f32_16x16x32_bf16 v[248:251], v[196:199], v[236:239], v[248:251]
	s_nop 7
	v_cvt_pk_bf16_f32 v176, v240, v241
	v_cvt_pk_bf16_f32 v177, v242, v243
	v_cvt_pk_bf16_f32 v184, v244, v245
	v_cvt_pk_bf16_f32 v185, v246, v247
	v_cvt_pk_bf16_f32 v192, v248, v249
	v_cvt_pk_bf16_f32 v193, v250, v251
	ds_write_b64 v127, v[176:177] offset:18432
	ds_write_b64 v127, v[184:185] offset:0
	ds_write_b16 v151, v184 offset:9216
	ds_write_b16_d16_hi v151, v184 offset:9360
	ds_write_b16 v151, v185 offset:9504
	ds_write_b16_d16_hi v151, v185 offset:9648
	ds_write_b64 v129, v[102:103] offset:18432
	ds_write_b64 v129, v[192:193] offset:0
	ds_write_b16 v152, v192 offset:9216
	ds_write_b16_d16_hi v152, v192 offset:9360
	ds_write_b16 v152, v193 offset:9504
	ds_write_b16_d16_hi v152, v193 offset:9648
	s_waitcnt lgkmcnt(0)
	s_barrier
	ds_read_b64 v[242:243], v127 offset:18432
	ds_read_b128 v[176:179], v173 offset:0
	ds_read_b128 v[224:227], v107 offset:18432
	ds_read_b128 v[180:183], v173 offset:64
	ds_read_b128 v[228:231], v107 offset:18496
	s_waitcnt lgkmcnt(4)
	v_lshlrev_b32_e32 v240, 16, v242
	v_and_b32_e32 v241, 0xffff0000, v242
	v_lshlrev_b32_e32 v242, 16, v243
	v_and_b32_e32 v243, 0xffff0000, v243
	s_nop 1
	s_waitcnt lgkmcnt(2)
	v_mfma_f32_16x16x32_bf16 v[240:243], v[176:179], v[224:227], v[240:243]
	s_waitcnt lgkmcnt(0)
	v_mfma_f32_16x16x32_bf16 v[240:243], v[180:183], v[228:231], v[240:243]
	s_nop 7
	v_cvt_pk_bf16_f32 v176, v240, v241
	v_cvt_pk_bf16_f32 v177, v242, v243
	ds_write_b64 v97, v[176:177] offset:18432
	ds_write_b64 v98, v[102:103] offset:18432
	s_waitcnt lgkmcnt(0)
	s_barrier
	s_branch .La2_done
; __device__ __forceinline__ void st4_lds(LAS unsigned char* p, f32x4 v) { v2u w; w.x = pk2(v[0], v[1]); w.y = pk2(v[2], v[3]); *(LAS v2u*)p = w; }
; __device__ __forceinline__ f32x4 ld4_lds(const LAS unsigned char* p) { const v2u w = *(const LAS v2u*)p; return (f32x4){bflo(w.x), bfhi(w.x), bflo(w.y), bfhi(w.y)}; }
; #define LBAR() asm volatile("s_waitcnt lgkmcnt(0)\n\ts_barrier" ::: "memory")
; __device__ __forceinline__ void rwkv_chunk_group(Frame& F, int bc, unsigned long long& tsub) {
;     ...
;     for (int it = 0; it < 6; ++it) {
;         const int rM = (it & 1) ? L_AT : L_M, rMT = (it & 1) ? L_BT : L_MT, rTT = (it & 1) ? L_KT : L_TT;
;         const int wM = (it & 1) ? L_M : L_AT, wMT = (it & 1) ? L_MT : L_BT, wTT = (it & 1) ? L_TT : L_KT;
; #pragma unroll
;         for (int q = 0; q < 2; ++q) { const int tw = 2 * w + q, p0 = 16 * (tw >> 2), q0 = 16 * (tw & 3); const int o = (p0 + fr) * LD + (q0 + 4 * fq) * 2;
;             f32x4 tn = Z4, mn = Z4;
;             if (q0 <= p0) { tn = mm_tile(L + rM, LD, q0, L + rTT, LD, p0, 2, ld4_lds(L + rTT + o), fr, fq);
;                           }
;             if (q0 >= p0 && it < 5) mn = mm_tile(L + rMT, LD, q0, L + rM, LD, p0, 2, Z4, fr, fq);
;             st4_lds(L + wTT + o, tn); if (it < 5) { st4_lds(L + wM + o, mn); st4t_lds(L + wMT, p0 + fr, q0 + 4 * fq, mn); } }
;         LBAR();
;     }
.La2_TFTx:
	s_and_b64 vcc, exec, s[90:91]
	s_cbranch_vccz .La2_TFTF
	ds_read_b64 v[242:243], v97 offset:18432
	ds_read_b64 v[246:247], v98 offset:18432
	ds_read_b128 v[176:179], v175 offset:0
	ds_read_b128 v[224:227], v132 offset:18432
	ds_read_b128 v[184:187], v96 offset:0
	ds_read_b128 v[192:195], v96 offset:9216
	ds_read_b128 v[232:235], v132 offset:0
	ds_read_b128 v[180:183], v175 offset:64
	ds_read_b128 v[228:231], v132 offset:18496
	ds_read_b128 v[188:191], v96 offset:64
	ds_read_b128 v[196:199], v96 offset:9280
	ds_read_b128 v[236:239], v132 offset:64
	s_waitcnt lgkmcnt(11)
	v_lshlrev_b32_e32 v240, 16, v242
	v_and_b32_e32 v241, 0xffff0000, v242
	v_lshlrev_b32_e32 v242, 16, v243
	v_and_b32_e32 v243, 0xffff0000, v243
	s_waitcnt lgkmcnt(10)
	v_lshlrev_b32_e32 v244, 16, v246
	v_and_b32_e32 v245, 0xffff0000, v246
	v_lshlrev_b32_e32 v246, 16, v247
	v_and_b32_e32 v247, 0xffff0000, v247
	s_nop 1
	s_waitcnt lgkmcnt(8)
	v_mfma_f32_16x16x32_bf16 v[240:243], v[176:179], v[224:227], v[240:243]
	s_waitcnt lgkmcnt(7)
	v_mfma_f32_16x16x32_bf16 v[244:247], v[184:187], v[224:227], v[244:247]
	s_waitcnt lgkmcnt(5)
	v_mfma_f32_16x16x32_bf16 v[248:251], v[192:195], v[232:235], 0
	s_waitcnt lgkmcnt(3)
	v_mfma_f32_16x16x32_bf16 v[240:243], v[180:183], v[228:231], v[240:243]
	s_waitcnt lgkmcnt(2)
	v_mfma_f32_16x16x32_bf16 v[244:247], v[188:191], v[228:231], v[244:247]
	s_waitcnt lgkmcnt(0)
	v_mfma_f32_16x16x32_bf16 v[248:251], v[196:199], v[236:239], v[248:251]
	s_nop 7
	v_cvt_pk_bf16_f32 v176, v240, v241
	v_cvt_pk_bf16_f32 v177, v242, v243
	v_cvt_pk_bf16_f32 v184, v244, v245
	v_cvt_pk_bf16_f32 v185, v246, v247
	v_cvt_pk_bf16_f32 v192, v248, v249
	v_cvt_pk_bf16_f32 v193, v250, v251
	ds_write_b64 v127, v[176:177] offset:18432
	ds_write_b64 v127, v[102:103] offset:0
	ds_write_b16 v151, v102 offset:9216
	ds_write_b16_d16_hi v151, v102 offset:9360
	ds_write_b16 v151, v103 offset:9504
	ds_write_b16_d16_hi v151, v103 offset:9648
	ds_write_b64 v129, v[184:185] offset:18432
	ds_write_b64 v129, v[192:193] offset:0
	ds_write_b16 v152, v192 offset:9216
	ds_write_b16_d16_hi v152, v192 offset:9360
	ds_write_b16 v152, v193 offset:9504
	ds_write_b16_d16_hi v152, v193 offset:9648
	s_waitcnt lgkmcnt(0)
	s_barrier
	ds_read_b64 v[242:243], v127 offset:18432
	ds_read_b64 v[246:247], v129 offset:18432
	ds_read_b128 v[176:179], v173 offset:0
	ds_read_b128 v[224:227], v107 offset:18432
	ds_read_b128 v[184:187], v174 offset:0
	ds_read_b128 v[192:195], v174 offset:9216
	ds_read_b128 v[232:235], v107 offset:0
	ds_read_b128 v[180:183], v173 offset:64
	ds_read_b128 v[228:231], v107 offset:18496
	ds_read_b128 v[188:191], v174 offset:64
	ds_read_b128 v[196:199], v174 offset:9280
	ds_read_b128 v[236:239], v107 offset:64
	s_waitcnt lgkmcnt(11)
	v_lshlrev_b32_e32 v240, 16, v242
	v_and_b32_e32 v241, 0xffff0000, v242
	v_lshlrev_b32_e32 v242, 16, v243
	v_and_b32_e32 v243, 0xffff0000, v243
	s_waitcnt lgkmcnt(10)
	v_lshlrev_b32_e32 v244, 16, v246
	v_and_b32_e32 v245, 0xffff0000, v246
	v_lshlrev_b32_e32 v246, 16, v247
	v_and_b32_e32 v247, 0xffff0000, v247
	s_nop 1
	s_waitcnt lgkmcnt(8)
	v_mfma_f32_16x16x32_bf16 v[240:243], v[176:179], v[224:227], v[240:243]
	s_waitcnt lgkmcnt(7)
	v_mfma_f32_16x16x32_bf16 v[244:247], v[184:187], v[224:227], v[244:247]
	s_waitcnt lgkmcnt(5)
	v_mfma_f32_16x16x32_bf16 v[248:251], v[192:195], v[232:235], 0
	s_waitcnt lgkmcnt(3)
	v_mfma_f32_16x16x32_bf16 v[240:243], v[180:183], v[228:231], v[240:243]
	s_waitcnt lgkmcnt(2)
	v_mfma_f32_16x16x32_bf16 v[244:247], v[188:191], v[228:231], v[244:247]
	s_waitcnt lgkmcnt(0)
	v_mfma_f32_16x16x32_bf16 v[248:251], v[196:199], v[236:239], v[248:251]
	s_nop 7
	v_cvt_pk_bf16_f32 v176, v240, v241
	v_cvt_pk_bf16_f32 v177, v242, v243
	v_cvt_pk_bf16_f32 v184, v244, v245
	v_cvt_pk_bf16_f32 v185, v246, v247
	v_cvt_pk_bf16_f32 v192, v248, v249
	v_cvt_pk_bf16_f32 v193, v250, v251
	ds_write_b64 v97, v[176:177] offset:18432
	ds_write_b64 v97, v[102:103] offset:0
	ds_write_b16 v148, v102 offset:0
	ds_write_b16_d16_hi v148, v102 offset:144
	ds_write_b16 v148, v103 offset:288
	ds_write_b16_d16_hi v148, v103 offset:432
	ds_write_b64 v98, v[184:185] offset:18432
	ds_write_b64 v98, v[192:193] offset:0
	ds_write_b16 v149, v192 offset:0
	ds_write_b16_d16_hi v149, v192 offset:144
	ds_write_b16 v149, v193 offset:288
	ds_write_b16_d16_hi v149, v193 offset:432
	s_waitcnt lgkmcnt(0)
	s_barrier
	ds_read_b64 v[242:243], v97 offset:18432
	ds_read_b64 v[246:247], v98 offset:18432
	ds_read_b128 v[176:179], v175 offset:0
	ds_read_b128 v[224:227], v132 offset:18432
	ds_read_b128 v[184:187], v96 offset:0
	ds_read_b128 v[192:195], v96 offset:9216
	ds_read_b128 v[232:235], v132 offset:0
	ds_read_b128 v[180:183], v175 offset:64
	ds_read_b128 v[228:231], v132 offset:18496
	ds_read_b128 v[188:191], v96 offset:64
	ds_read_b128 v[196:199], v96 offset:9280
	ds_read_b128 v[236:239], v132 offset:64
	s_waitcnt lgkmcnt(11)
	v_lshlrev_b32_e32 v240, 16, v242
	v_and_b32_e32 v241, 0xffff0000, v242
	v_lshlrev_b32_e32 v242, 16, v243
	v_and_b32_e32 v243, 0xffff0000, v243
	s_waitcnt lgkmcnt(10)
	v_lshlrev_b32_e32 v244, 16, v246
	v_and_b32_e32 v245, 0xffff0000, v246
	v_lshlrev_b32_e32 v246, 16, v247
	v_and_b32_e32 v247, 0xffff0000, v247
	s_nop 1
	s_waitcnt lgkmcnt(8)
	v_mfma_f32_16x16x32_bf16 v[240:243], v[176:179], v[224:227], v[240:243]
	s_waitcnt lgkmcnt(7)
	v_mfma_f32_16x16x32_bf16 v[244:247], v[184:187], v[224:227], v[244:247]
	s_waitcnt lgkmcnt(5)
	v_mfma_f32_16x16x32_bf16 v[248:251], v[192:195], v[232:235], 0
	s_waitcnt lgkmcnt(3)
	v_mfma_f32_16x16x32_bf16 v[240:243], v[180:183], v[228:231], v[240:243]
	s_waitcnt lgkmcnt(2)
	v_mfma_f32_16x16x32_bf16 v[244:247], v[188:191], v[228:231], v[244:247]
	s_waitcnt lgkmcnt(0)
	v_mfma_f32_16x16x32_bf16 v[248:251], v[196:199], v[236:239], v[248:251]
	s_nop 7
	v_cvt_pk_bf16_f32 v176, v240, v241
	v_cvt_pk_bf16_f32 v177, v242, v243
	v_cvt_pk_bf16_f32 v184, v244, v245
	v_cvt_pk_bf16_f32 v185, v246, v247
	v_cvt_pk_bf16_f32 v192, v248, v249
	v_cvt_pk_bf16_f32 v193, v250, v251
	ds_write_b64 v127, v[176:177] offset:18432
	ds_write_b64 v127, v[102:103] offset:0
	ds_write_b16 v151, v102 offset:9216
	ds_write_b16_d16_hi v151, v102 offset:9360
	ds_write_b16 v151, v103 offset:9504
	ds_write_b16_d16_hi v151, v103 offset:9648
	ds_write_b64 v129, v[184:185] offset:18432
	ds_write_b64 v129, v[192:193] offset:0
	ds_write_b16 v152, v192 offset:9216
	ds_write_b16_d16_hi v152, v192 offset:9360
	ds_write_b16 v152, v193 offset:9504
	ds_write_b16_d16_hi v152, v193 offset:9648
	s_waitcnt lgkmcnt(0)
	s_barrier
; __device__ __forceinline__ void st4_lds(LAS unsigned char* p, f32x4 v) { v2u w; w.x = pk2(v[0], v[1]); w.y = pk2(v[2], v[3]); *(LAS v2u*)p = w; }
; __device__ __forceinline__ f32x4 ld4_lds(const LAS unsigned char* p) { const v2u w = *(const LAS v2u*)p; return (f32x4){bflo(w.x), bfhi(w.x), bflo(w.y), bfhi(w.y)}; }
; #define LBAR() asm volatile("s_waitcnt lgkmcnt(0)\n\ts_barrier" ::: "memory")
; __device__ __forceinline__ void rwkv_chunk_group(Frame& F, int bc, unsigned long long& tsub) {
;     ...
;     for (int it = 0; it < 6; ++it) {
;         const int rM = (it & 1) ? L_AT : L_M, rMT = (it & 1) ? L_BT : L_MT, rTT = (it & 1) ? L_KT : L_TT;
;         const int wM = (it & 1) ? L_M : L_AT, wMT = (it & 1) ? L_MT : L_BT, wTT = (it & 1) ? L_TT : L_KT;
; #pragma unroll
;         for (int q = 0; q < 2; ++q) { const int tw = 2 * w + q, p0 = 16 * (tw >> 2), q0 = 16 * (tw & 3); const int o = (p0 + fr) * LD + (q0 + 4 * fq) * 2;
;             f32x4 tn = Z4, mn = Z4;
;             if (q0 <= p0) { tn = mm_tile(L + rM, LD, q0, L + rTT, LD, p0, 2, ld4_lds(L + rTT + o), fr, fq);
;                           }
;             if (q0 >= p0 && it < 5) mn = mm_tile(L + rMT, LD, q0, L + rM, LD, p0, 2, Z4, fr, fq);
;             st4_lds(L + wTT + o, tn); if (it < 5) { st4_lds(L + wM + o, mn); st4t_lds(L + wMT, p0 + fr, q0 + 4 * fq, mn); } }
;         LBAR();
;     }
	ds_read_b64 v[242:243], v127 offset:18432
	ds_read_b64 v[246:247], v129 offset:18432
	ds_read_b128 v[176:179], v173 offset:0
	ds_read_b128 v[224:227], v107 offset:18432
	ds_read_b128 v[184:187], v174 offset:0
	ds_read_b128 v[192:195], v174 offset:9216
	ds_read_b128 v[232:235], v107 offset:0
	ds_read_b128 v[180:183], v173 offset:64
	ds_read_b128 v[228:231], v107 offset:18496
	ds_read_b128 v[188:191], v174 offset:64
	ds_read_b128 v[196:199], v174 offset:9280
	ds_read_b128 v[236:239], v107 offset:64
	s_waitcnt lgkmcnt(11)
	v_lshlrev_b32_e32 v240, 16, v242
	v_and_b32_e32 v241, 0xffff0000, v242
	v_lshlrev_b32_e32 v242, 16, v243
	v_and_b32_e32 v243, 0xffff0000, v243
	s_waitcnt lgkmcnt(10)
	v_lshlrev_b32_e32 v244, 16, v246
	v_and_b32_e32 v245, 0xffff0000, v246
	v_lshlrev_b32_e32 v246, 16, v247
	v_and_b32_e32 v247, 0xffff0000, v247
	s_nop 1
	s_waitcnt lgkmcnt(8)
	v_mfma_f32_16x16x32_bf16 v[240:243], v[176:179], v[224:227], v[240:243]
	s_waitcnt lgkmcnt(7)
	v_mfma_f32_16x16x32_bf16 v[244:247], v[184:187], v[224:227], v[244:247]
	s_waitcnt lgkmcnt(5)
	v_mfma_f32_16x16x32_bf16 v[248:251], v[192:195], v[232:235], 0
	s_waitcnt lgkmcnt(3)
	v_mfma_f32_16x16x32_bf16 v[240:243], v[180:183], v[228:231], v[240:243]
	s_waitcnt lgkmcnt(2)
	v_mfma_f32_16x16x32_bf16 v[244:247], v[188:191], v[228:231], v[244:247]
	s_waitcnt lgkmcnt(0)
	v_mfma_f32_16x16x32_bf16 v[248:251], v[196:199], v[236:239], v[248:251]
	s_nop 7
	v_cvt_pk_bf16_f32 v176, v240, v241
	v_cvt_pk_bf16_f32 v177, v242, v243
	v_cvt_pk_bf16_f32 v184, v244, v245
	v_cvt_pk_bf16_f32 v185, v246, v247
	v_cvt_pk_bf16_f32 v192, v248, v249
	v_cvt_pk_bf16_f32 v193, v250, v251
	ds_write_b64 v97, v[176:177] offset:18432
	ds_write_b64 v97, v[102:103] offset:0
	ds_write_b16 v148, v102 offset:0
	ds_write_b16_d16_hi v148, v102 offset:144
	ds_write_b16 v148, v103 offset:288
	ds_write_b16_d16_hi v148, v103 offset:432
	ds_write_b64 v98, v[184:185] offset:18432
	ds_write_b64 v98, v[192:193] offset:0
	ds_write_b16 v149, v192 offset:0
	ds_write_b16_d16_hi v149, v192 offset:144
	ds_write_b16 v149, v193 offset:288
	ds_write_b16_d16_hi v149, v193 offset:432
	s_waitcnt lgkmcnt(0)
	s_barrier
	ds_read_b64 v[242:243], v97 offset:18432
	ds_read_b64 v[246:247], v98 offset:18432
	ds_read_b128 v[176:179], v175 offset:0
	ds_read_b128 v[224:227], v132 offset:18432
	ds_read_b128 v[184:187], v96 offset:0
	ds_read_b128 v[192:195], v96 offset:9216
	ds_read_b128 v[232:235], v132 offset:0
	ds_read_b128 v[180:183], v175 offset:64
	ds_read_b128 v[228:231], v132 offset:18496
	ds_read_b128 v[188:191], v96 offset:64
	ds_read_b128 v[196:199], v96 offset:9280
	ds_read_b128 v[236:239], v132 offset:64
	s_waitcnt lgkmcnt(11)
	v_lshlrev_b32_e32 v240, 16, v242
	v_and_b32_e32 v241, 0xffff0000, v242
	v_lshlrev_b32_e32 v242, 16, v243
	v_and_b32_e32 v243, 0xffff0000, v243
	s_waitcnt lgkmcnt(10)
	v_lshlrev_b32_e32 v244, 16, v246
	v_and_b32_e32 v245, 0xffff0000, v246
	v_lshlrev_b32_e32 v246, 16, v247
	v_and_b32_e32 v247, 0xffff0000, v247
	s_nop 1
	s_waitcnt lgkmcnt(8)
	v_mfma_f32_16x16x32_bf16 v[240:243], v[176:179], v[224:227], v[240:243]
	s_waitcnt lgkmcnt(7)
	v_mfma_f32_16x16x32_bf16 v[244:247], v[184:187], v[224:227], v[244:247]
	s_waitcnt lgkmcnt(5)
	v_mfma_f32_16x16x32_bf16 v[248:251], v[192:195], v[232:235], 0
	s_waitcnt lgkmcnt(3)
	v_mfma_f32_16x16x32_bf16 v[240:243], v[180:183], v[228:231], v[240:243]
	s_waitcnt lgkmcnt(2)
	v_mfma_f32_16x16x32_bf16 v[244:247], v[188:191], v[228:231], v[244:247]
	s_waitcnt lgkmcnt(0)
	v_mfma_f32_16x16x32_bf16 v[248:251], v[196:199], v[236:239], v[248:251]
	s_nop 7
	v_cvt_pk_bf16_f32 v176, v240, v241
	v_cvt_pk_bf16_f32 v177, v242, v243
	v_cvt_pk_bf16_f32 v184, v244, v245
	v_cvt_pk_bf16_f32 v185, v246, v247
	v_cvt_pk_bf16_f32 v192, v248, v249
	v_cvt_pk_bf16_f32 v193, v250, v251
	ds_write_b64 v127, v[176:177] offset:18432
	ds_write_b64 v127, v[102:103] offset:0
	ds_write_b16 v151, v102 offset:9216
	ds_write_b16_d16_hi v151, v102 offset:9360
	ds_write_b16 v151, v103 offset:9504
	ds_write_b16_d16_hi v151, v103 offset:9648
	ds_write_b64 v129, v[184:185] offset:18432
	ds_write_b64 v129, v[192:193] offset:0
	ds_write_b16 v152, v192 offset:9216
	ds_write_b16_d16_hi v152, v192 offset:9360
	ds_write_b16 v152, v193 offset:9504
	ds_write_b16_d16_hi v152, v193 offset:9648
	s_waitcnt lgkmcnt(0)
	s_barrier
	ds_read_b64 v[242:243], v127 offset:18432
	ds_read_b64 v[246:247], v129 offset:18432
	ds_read_b128 v[176:179], v173 offset:0
	ds_read_b128 v[224:227], v107 offset:18432
	ds_read_b128 v[184:187], v174 offset:0
	ds_read_b128 v[180:183], v173 offset:64
	ds_read_b128 v[228:231], v107 offset:18496
	ds_read_b128 v[188:191], v174 offset:64
	s_waitcnt lgkmcnt(7)
	v_lshlrev_b32_e32 v240, 16, v242
	v_and_b32_e32 v241, 0xffff0000, v242
	v_lshlrev_b32_e32 v242, 16, v243
	v_and_b32_e32 v243, 0xffff0000, v243
	s_waitcnt lgkmcnt(6)
	v_lshlrev_b32_e32 v244, 16, v246
	v_and_b32_e32 v245, 0xffff0000, v246
	v_lshlrev_b32_e32 v246, 16, v247
	v_and_b32_e32 v247, 0xffff0000, v247
	s_nop 1
	s_waitcnt lgkmcnt(4)
	v_mfma_f32_16x16x32_bf16 v[240:243], v[176:179], v[224:227], v[240:243]
	s_waitcnt lgkmcnt(3)
	v_mfma_f32_16x16x32_bf16 v[244:247], v[184:187], v[224:227], v[244:247]
	s_waitcnt lgkmcnt(1)
	v_mfma_f32_16x16x32_bf16 v[240:243], v[180:183], v[228:231], v[240:243]
	s_waitcnt lgkmcnt(0)
	v_mfma_f32_16x16x32_bf16 v[244:247], v[188:191], v[228:231], v[244:247]
	s_nop 7
	v_cvt_pk_bf16_f32 v176, v240, v241
	v_cvt_pk_bf16_f32 v177, v242, v243
	v_cvt_pk_bf16_f32 v184, v244, v245
	v_cvt_pk_bf16_f32 v185, v246, v247
	ds_write_b64 v97, v[176:177] offset:18432
	ds_write_b64 v98, v[184:185] offset:18432
	s_waitcnt lgkmcnt(0)
	s_barrier
	s_branch .La2_done
; __device__ __forceinline__ void st4_lds(LAS unsigned char* p, f32x4 v) { v2u w; w.x = pk2(v[0], v[1]); w.y = pk2(v[2], v[3]); *(LAS v2u*)p = w; }
; __device__ __forceinline__ f32x4 ld4_lds(const LAS unsigned char* p) { const v2u w = *(const LAS v2u*)p; return (f32x4){bflo(w.x), bfhi(w.x), bflo(w.y), bfhi(w.y)}; }
; #define LBAR() asm volatile("s_waitcnt lgkmcnt(0)\n\ts_barrier" ::: "memory")
; __device__ __forceinline__ void rwkv_chunk_group(Frame& F, int bc, unsigned long long& tsub) {
;     ...
;     for (int it = 0; it < 6; ++it) {
;         const int rM = (it & 1) ? L_AT : L_M, rMT = (it & 1) ? L_BT : L_MT, rTT = (it & 1) ? L_KT : L_TT;
;         const int wM = (it & 1) ? L_M : L_AT, wMT = (it & 1) ? L_MT : L_BT, wTT = (it & 1) ? L_TT : L_KT;
; #pragma unroll
;         for (int q = 0; q < 2; ++q) { const int tw = 2 * w + q, p0 = 16 * (tw >> 2), q0 = 16 * (tw & 3); const int o = (p0 + fr) * LD + (q0 + 4 * fq) * 2;
;             f32x4 tn = Z4, mn = Z4;
;             if (q0 <= p0) { tn = mm_tile(L + rM, LD, q0, L + rTT, LD, p0, 2, ld4_lds(L + rTT + o), fr, fq);
;                           }
;             if (q0 >= p0 && it < 5) mn = mm_tile(L + rMT, LD, q0, L + rM, LD, p0, 2, Z4, fr, fq);
;             st4_lds(L + wTT + o, tn); if (it < 5) { st4_lds(L + wM + o, mn); st4t_lds(L + wMT, p0 + fr, q0 + 4 * fq, mn); } }
;         LBAR();
;     }
.La2_TFTF:
	ds_read_b64 v[242:243], v97 offset:18432
	ds_read_b64 v[246:247], v98 offset:18432
	ds_read_b128 v[176:179], v175 offset:0
	ds_read_b128 v[224:227], v132 offset:18432
	ds_read_b128 v[184:187], v96 offset:0
	ds_read_b128 v[180:183], v175 offset:64
	ds_read_b128 v[228:231], v132 offset:18496
	ds_read_b128 v[188:191], v96 offset:64
	s_waitcnt lgkmcnt(7)
	v_lshlrev_b32_e32 v240, 16, v242
	v_and_b32_e32 v241, 0xffff0000, v242
	v_lshlrev_b32_e32 v242, 16, v243
	v_and_b32_e32 v243, 0xffff0000, v243
	s_waitcnt lgkmcnt(6)
	v_lshlrev_b32_e32 v244, 16, v246
	v_and_b32_e32 v245, 0xffff0000, v246
	v_lshlrev_b32_e32 v246, 16, v247
	v_and_b32_e32 v247, 0xffff0000, v247
	s_nop 1
	s_waitcnt lgkmcnt(4)
	v_mfma_f32_16x16x32_bf16 v[240:243], v[176:179], v[224:227], v[240:243]
	s_waitcnt lgkmcnt(3)
	v_mfma_f32_16x16x32_bf16 v[244:247], v[184:187], v[224:227], v[244:247]
	s_waitcnt lgkmcnt(1)
	v_mfma_f32_16x16x32_bf16 v[240:243], v[180:183], v[228:231], v[240:243]
	s_waitcnt lgkmcnt(0)
	v_mfma_f32_16x16x32_bf16 v[244:247], v[188:191], v[228:231], v[244:247]
	s_nop 7
	v_cvt_pk_bf16_f32 v176, v240, v241
	v_cvt_pk_bf16_f32 v177, v242, v243
	v_cvt_pk_bf16_f32 v184, v244, v245
	v_cvt_pk_bf16_f32 v185, v246, v247
	ds_write_b64 v127, v[176:177] offset:18432
	ds_write_b64 v127, v[102:103] offset:0
	ds_write_b16 v151, v102 offset:9216
	ds_write_b16_d16_hi v151, v102 offset:9360
	ds_write_b16 v151, v103 offset:9504
	ds_write_b16_d16_hi v151, v103 offset:9648
	ds_write_b64 v129, v[184:185] offset:18432
	ds_write_b64 v129, v[102:103] offset:0
	ds_write_b16 v152, v102 offset:9216
	ds_write_b16_d16_hi v152, v102 offset:9360
	ds_write_b16 v152, v103 offset:9504
	ds_write_b16_d16_hi v152, v103 offset:9648
	s_waitcnt lgkmcnt(0)
	s_barrier
	ds_read_b64 v[242:243], v127 offset:18432
	ds_read_b64 v[246:247], v129 offset:18432
	ds_read_b128 v[176:179], v173 offset:0
	ds_read_b128 v[224:227], v107 offset:18432
	ds_read_b128 v[184:187], v174 offset:0
	ds_read_b128 v[180:183], v173 offset:64
	ds_read_b128 v[228:231], v107 offset:18496
	ds_read_b128 v[188:191], v174 offset:64
	s_waitcnt lgkmcnt(7)
	v_lshlrev_b32_e32 v240, 16, v242
	v_and_b32_e32 v241, 0xffff0000, v242
	v_lshlrev_b32_e32 v242, 16, v243
	v_and_b32_e32 v243, 0xffff0000, v243
	s_waitcnt lgkmcnt(6)
	v_lshlrev_b32_e32 v244, 16, v246
	v_and_b32_e32 v245, 0xffff0000, v246
	v_lshlrev_b32_e32 v246, 16, v247
	v_and_b32_e32 v247, 0xffff0000, v247
	s_nop 1
	s_waitcnt lgkmcnt(4)
	v_mfma_f32_16x16x32_bf16 v[240:243], v[176:179], v[224:227], v[240:243]
	s_waitcnt lgkmcnt(3)
	v_mfma_f32_16x16x32_bf16 v[244:247], v[184:187], v[224:227], v[244:247]
	s_waitcnt lgkmcnt(1)
	v_mfma_f32_16x16x32_bf16 v[240:243], v[180:183], v[228:231], v[240:243]
	s_waitcnt lgkmcnt(0)
	v_mfma_f32_16x16x32_bf16 v[244:247], v[188:191], v[228:231], v[244:247]
	s_nop 7
	v_cvt_pk_bf16_f32 v176, v240, v241
	v_cvt_pk_bf16_f32 v177, v242, v243
	v_cvt_pk_bf16_f32 v184, v244, v245
	v_cvt_pk_bf16_f32 v185, v246, v247
	ds_write_b64 v97, v[176:177] offset:18432
	ds_write_b64 v97, v[102:103] offset:0
	ds_write_b16 v148, v102 offset:0
	ds_write_b16_d16_hi v148, v102 offset:144
	ds_write_b16 v148, v103 offset:288
	ds_write_b16_d16_hi v148, v103 offset:432
	ds_write_b64 v98, v[184:185] offset:18432
	ds_write_b64 v98, v[102:103] offset:0
	ds_write_b16 v149, v102 offset:0
	ds_write_b16_d16_hi v149, v102 offset:144
	ds_write_b16 v149, v103 offset:288
	ds_write_b16_d16_hi v149, v103 offset:432
	s_waitcnt lgkmcnt(0)
	s_barrier
	ds_read_b64 v[242:243], v97 offset:18432
	ds_read_b64 v[246:247], v98 offset:18432
	ds_read_b128 v[176:179], v175 offset:0
	ds_read_b128 v[224:227], v132 offset:18432
	ds_read_b128 v[184:187], v96 offset:0
	ds_read_b128 v[180:183], v175 offset:64
	ds_read_b128 v[228:231], v132 offset:18496
	ds_read_b128 v[188:191], v96 offset:64
	s_waitcnt lgkmcnt(7)
	v_lshlrev_b32_e32 v240, 16, v242
	v_and_b32_e32 v241, 0xffff0000, v242
	v_lshlrev_b32_e32 v242, 16, v243
	v_and_b32_e32 v243, 0xffff0000, v243
	s_waitcnt lgkmcnt(6)
	v_lshlrev_b32_e32 v244, 16, v246
	v_and_b32_e32 v245, 0xffff0000, v246
	v_lshlrev_b32_e32 v246, 16, v247
	v_and_b32_e32 v247, 0xffff0000, v247
	s_nop 1
	s_waitcnt lgkmcnt(4)
	v_mfma_f32_16x16x32_bf16 v[240:243], v[176:179], v[224:227], v[240:243]
	s_waitcnt lgkmcnt(3)
	v_mfma_f32_16x16x32_bf16 v[244:247], v[184:187], v[224:227], v[244:247]
	s_waitcnt lgkmcnt(1)
	v_mfma_f32_16x16x32_bf16 v[240:243], v[180:183], v[228:231], v[240:243]
	s_waitcnt lgkmcnt(0)
	v_mfma_f32_16x16x32_bf16 v[244:247], v[188:191], v[228:231], v[244:247]
	s_nop 7
	v_cvt_pk_bf16_f32 v176, v240, v241
	v_cvt_pk_bf16_f32 v177, v242, v243
	v_cvt_pk_bf16_f32 v184, v244, v245
	v_cvt_pk_bf16_f32 v185, v246, v247
	ds_write_b64 v127, v[176:177] offset:18432
	ds_write_b64 v127, v[102:103] offset:0
	ds_write_b16 v151, v102 offset:9216
	ds_write_b16_d16_hi v151, v102 offset:9360
	ds_write_b16 v151, v103 offset:9504
	ds_write_b16_d16_hi v151, v103 offset:9648
	ds_write_b64 v129, v[184:185] offset:18432
	ds_write_b64 v129, v[102:103] offset:0
	ds_write_b16 v152, v102 offset:9216
	ds_write_b16_d16_hi v152, v102 offset:9360
	ds_write_b16 v152, v103 offset:9504
	ds_write_b16_d16_hi v152, v103 offset:9648
	s_waitcnt lgkmcnt(0)
	s_barrier
; __device__ __forceinline__ void st4_lds(LAS unsigned char* p, f32x4 v) { v2u w; w.x = pk2(v[0], v[1]); w.y = pk2(v[2], v[3]); *(LAS v2u*)p = w; }
; __device__ __forceinline__ f32x4 ld4_lds(const LAS unsigned char* p) { const v2u w = *(const LAS v2u*)p; return (f32x4){bflo(w.x), bfhi(w.x), bflo(w.y), bfhi(w.y)}; }
; #define LBAR() asm volatile("s_waitcnt lgkmcnt(0)\n\ts_barrier" ::: "memory")
; __device__ __forceinline__ void rwkv_chunk_group(Frame& F, int bc, unsigned long long& tsub) {
;     ...
;     for (int it = 0; it < 6; ++it) {
;         const int rM = (it & 1) ? L_AT : L_M, rMT = (it & 1) ? L_BT : L_MT, rTT = (it & 1) ? L_KT : L_TT;
;         const int wM = (it & 1) ? L_M : L_AT, wMT = (it & 1) ? L_MT : L_BT, wTT = (it & 1) ? L_TT : L_KT;
; #pragma unroll
;         for (int q = 0; q < 2; ++q) { const int tw = 2 * w + q, p0 = 16 * (tw >> 2), q0 = 16 * (tw & 3); const int o = (p0 + fr) * LD + (q0 + 4 * fq) * 2;
;             f32x4 tn = Z4, mn = Z4;
;             if (q0 <= p0) { tn = mm_tile(L + rM, LD, q0, L + rTT, LD, p0, 2, ld4_lds(L + rTT + o), fr, fq);
;                           }
;             if (q0 >= p0 && it < 5) mn = mm_tile(L + rMT, LD, q0, L + rM, LD, p0, 2, Z4, fr, fq);
;             st4_lds(L + wTT + o, tn); if (it < 5) { st4_lds(L + wM + o, mn); st4t_lds(L + wMT, p0 + fr, q0 + 4 * fq, mn); } }
;         LBAR();
;     }
	ds_read_b64 v[242:243], v127 offset:18432
	ds_read_b64 v[246:247], v129 offset:18432
	ds_read_b128 v[176:179], v173 offset:0
	ds_read_b128 v[224:227], v107 offset:18432
	ds_read_b128 v[184:187], v174 offset:0
	ds_read_b128 v[180:183], v173 offset:64
	ds_read_b128 v[228:231], v107 offset:18496
	ds_read_b128 v[188:191], v174 offset:64
	s_waitcnt lgkmcnt(7)
	v_lshlrev_b32_e32 v240, 16, v242
	v_and_b32_e32 v241, 0xffff0000, v242
	v_lshlrev_b32_e32 v242, 16, v243
	v_and_b32_e32 v243, 0xffff0000, v243
	s_waitcnt lgkmcnt(6)
	v_lshlrev_b32_e32 v244, 16, v246
	v_and_b32_e32 v245, 0xffff0000, v246
	v_lshlrev_b32_e32 v246, 16, v247
	v_and_b32_e32 v247, 0xffff0000, v247
	s_nop 1
	s_waitcnt lgkmcnt(4)
	v_mfma_f32_16x16x32_bf16 v[240:243], v[176:179], v[224:227], v[240:243]
	s_waitcnt lgkmcnt(3)
	v_mfma_f32_16x16x32_bf16 v[244:247], v[184:187], v[224:227], v[244:247]
	s_waitcnt lgkmcnt(1)
	v_mfma_f32_16x16x32_bf16 v[240:243], v[180:183], v[228:231], v[240:243]
	s_waitcnt lgkmcnt(0)
	v_mfma_f32_16x16x32_bf16 v[244:247], v[188:191], v[228:231], v[244:247]
	s_nop 7
	v_cvt_pk_bf16_f32 v176, v240, v241
	v_cvt_pk_bf16_f32 v177, v242, v243
	v_cvt_pk_bf16_f32 v184, v244, v245
	v_cvt_pk_bf16_f32 v185, v246, v247
	ds_write_b64 v97, v[176:177] offset:18432
	ds_write_b64 v97, v[102:103] offset:0
	ds_write_b16 v148, v102 offset:0
	ds_write_b16_d16_hi v148, v102 offset:144
	ds_write_b16 v148, v103 offset:288
	ds_write_b16_d16_hi v148, v103 offset:432
	ds_write_b64 v98, v[184:185] offset:18432
	ds_write_b64 v98, v[102:103] offset:0
	ds_write_b16 v149, v102 offset:0
	ds_write_b16_d16_hi v149, v102 offset:144
	ds_write_b16 v149, v103 offset:288
	ds_write_b16_d16_hi v149, v103 offset:432
	s_waitcnt lgkmcnt(0)
	s_barrier
	ds_read_b64 v[242:243], v97 offset:18432
	ds_read_b64 v[246:247], v98 offset:18432
	ds_read_b128 v[176:179], v175 offset:0
	ds_read_b128 v[224:227], v132 offset:18432
	ds_read_b128 v[184:187], v96 offset:0
	ds_read_b128 v[180:183], v175 offset:64
	ds_read_b128 v[228:231], v132 offset:18496
	ds_read_b128 v[188:191], v96 offset:64
	s_waitcnt lgkmcnt(7)
	v_lshlrev_b32_e32 v240, 16, v242
	v_and_b32_e32 v241, 0xffff0000, v242
	v_lshlrev_b32_e32 v242, 16, v243
	v_and_b32_e32 v243, 0xffff0000, v243
	s_waitcnt lgkmcnt(6)
	v_lshlrev_b32_e32 v244, 16, v246
	v_and_b32_e32 v245, 0xffff0000, v246
	v_lshlrev_b32_e32 v246, 16, v247
	v_and_b32_e32 v247, 0xffff0000, v247
	s_nop 1
	s_waitcnt lgkmcnt(4)
	v_mfma_f32_16x16x32_bf16 v[240:243], v[176:179], v[224:227], v[240:243]
	s_waitcnt lgkmcnt(3)
	v_mfma_f32_16x16x32_bf16 v[244:247], v[184:187], v[224:227], v[244:247]
	s_waitcnt lgkmcnt(1)
	v_mfma_f32_16x16x32_bf16 v[240:243], v[180:183], v[228:231], v[240:243]
	s_waitcnt lgkmcnt(0)
	v_mfma_f32_16x16x32_bf16 v[244:247], v[188:191], v[228:231], v[244:247]
	s_nop 7
	v_cvt_pk_bf16_f32 v176, v240, v241
	v_cvt_pk_bf16_f32 v177, v242, v243
	v_cvt_pk_bf16_f32 v184, v244, v245
	v_cvt_pk_bf16_f32 v185, v246, v247
	ds_write_b64 v127, v[176:177] offset:18432
	ds_write_b64 v127, v[102:103] offset:0
	ds_write_b16 v151, v102 offset:9216
	ds_write_b16_d16_hi v151, v102 offset:9360
	ds_write_b16 v151, v103 offset:9504
	ds_write_b16_d16_hi v151, v103 offset:9648
	ds_write_b64 v129, v[184:185] offset:18432
	ds_write_b64 v129, v[102:103] offset:0
	ds_write_b16 v152, v102 offset:9216
	ds_write_b16_d16_hi v152, v102 offset:9360
	ds_write_b16 v152, v103 offset:9504
	ds_write_b16_d16_hi v152, v103 offset:9648
	s_waitcnt lgkmcnt(0)
	s_barrier
	ds_read_b64 v[242:243], v127 offset:18432
	ds_read_b64 v[246:247], v129 offset:18432
	ds_read_b128 v[176:179], v173 offset:0
	ds_read_b128 v[224:227], v107 offset:18432
	ds_read_b128 v[184:187], v174 offset:0
	ds_read_b128 v[180:183], v173 offset:64
	ds_read_b128 v[228:231], v107 offset:18496
	ds_read_b128 v[188:191], v174 offset:64
	s_waitcnt lgkmcnt(7)
	v_lshlrev_b32_e32 v240, 16, v242
	v_and_b32_e32 v241, 0xffff0000, v242
	v_lshlrev_b32_e32 v242, 16, v243
	v_and_b32_e32 v243, 0xffff0000, v243
	s_waitcnt lgkmcnt(6)
	v_lshlrev_b32_e32 v244, 16, v246
	v_and_b32_e32 v245, 0xffff0000, v246
	v_lshlrev_b32_e32 v246, 16, v247
	v_and_b32_e32 v247, 0xffff0000, v247
	s_nop 1
	s_waitcnt lgkmcnt(4)
	v_mfma_f32_16x16x32_bf16 v[240:243], v[176:179], v[224:227], v[240:243]
	s_waitcnt lgkmcnt(3)
	v_mfma_f32_16x16x32_bf16 v[244:247], v[184:187], v[224:227], v[244:247]
	s_waitcnt lgkmcnt(1)
	v_mfma_f32_16x16x32_bf16 v[240:243], v[180:183], v[228:231], v[240:243]
	s_waitcnt lgkmcnt(0)
	v_mfma_f32_16x16x32_bf16 v[244:247], v[188:191], v[228:231], v[244:247]
	s_nop 7
	v_cvt_pk_bf16_f32 v176, v240, v241
	v_cvt_pk_bf16_f32 v177, v242, v243
	v_cvt_pk_bf16_f32 v184, v244, v245
	v_cvt_pk_bf16_f32 v185, v246, v247
	ds_write_b64 v97, v[176:177] offset:18432
	ds_write_b64 v98, v[184:185] offset:18432
	s_waitcnt lgkmcnt(0)
	s_barrier
	s_branch .La2_done
; __device__ __forceinline__ void st4_lds(LAS unsigned char* p, f32x4 v) { v2u w; w.x = pk2(v[0], v[1]); w.y = pk2(v[2], v[3]); *(LAS v2u*)p = w; }
; __device__ __forceinline__ f32x4 ld4_lds(const LAS unsigned char* p) { const v2u w = *(const LAS v2u*)p; return (f32x4){bflo(w.x), bfhi(w.x), bflo(w.y), bfhi(w.y)}; }
; #define LBAR() asm volatile("s_waitcnt lgkmcnt(0)\n\ts_barrier" ::: "memory")
; __device__ __forceinline__ void rwkv_chunk_group(Frame& F, int bc, unsigned long long& tsub) {
;     ...
;     for (int it = 0; it < 6; ++it) {
;         const int rM = (it & 1) ? L_AT : L_M, rMT = (it & 1) ? L_BT : L_MT, rTT = (it & 1) ? L_KT : L_TT;
;         const int wM = (it & 1) ? L_M : L_AT, wMT = (it & 1) ? L_MT : L_BT, wTT = (it & 1) ? L_TT : L_KT;
; #pragma unroll
;         for (int q = 0; q < 2; ++q) { const int tw = 2 * w + q, p0 = 16 * (tw >> 2), q0 = 16 * (tw & 3); const int o = (p0 + fr) * LD + (q0 + 4 * fq) * 2;
;             f32x4 tn = Z4, mn = Z4;
;             if (q0 <= p0) { tn = mm_tile(L + rM, LD, q0, L + rTT, LD, p0, 2, ld4_lds(L + rTT + o), fr, fq);
;                           }
;             if (q0 >= p0 && it < 5) mn = mm_tile(L + rMT, LD, q0, L + rM, LD, p0, 2, Z4, fr, fq);
;             st4_lds(L + wTT + o, tn); if (it < 5) { st4_lds(L + wM + o, mn); st4t_lds(L + wMT, p0 + fr, q0 + 4 * fq, mn); } }
;         LBAR();
;     }
.La2_FTFT:
	ds_read_b128 v[176:179], v175 offset:9216
	ds_read_b128 v[232:235], v132 offset:0
	ds_read_b128 v[184:187], v96 offset:9216
	ds_read_b128 v[180:183], v175 offset:9280
	ds_read_b128 v[236:239], v132 offset:64
	ds_read_b128 v[188:191], v96 offset:9280
	s_waitcnt lgkmcnt(4)
	v_mfma_f32_16x16x32_bf16 v[240:243], v[176:179], v[232:235], 0
	s_waitcnt lgkmcnt(3)
	v_mfma_f32_16x16x32_bf16 v[244:247], v[184:187], v[232:235], 0
	s_waitcnt lgkmcnt(1)
	v_mfma_f32_16x16x32_bf16 v[240:243], v[180:183], v[236:239], v[240:243]
	s_waitcnt lgkmcnt(0)
	v_mfma_f32_16x16x32_bf16 v[244:247], v[188:191], v[236:239], v[244:247]
	s_nop 7
	v_cvt_pk_bf16_f32 v176, v240, v241
	v_cvt_pk_bf16_f32 v177, v242, v243
	v_cvt_pk_bf16_f32 v184, v244, v245
	v_cvt_pk_bf16_f32 v185, v246, v247
	ds_write_b64 v127, v[102:103] offset:18432
	ds_write_b64 v127, v[176:177] offset:0
	ds_write_b16 v151, v176 offset:9216
	ds_write_b16_d16_hi v151, v176 offset:9360
	ds_write_b16 v151, v177 offset:9504
	ds_write_b16_d16_hi v151, v177 offset:9648
	ds_write_b64 v129, v[102:103] offset:18432
	ds_write_b64 v129, v[184:185] offset:0
	ds_write_b16 v152, v184 offset:9216
	ds_write_b16_d16_hi v152, v184 offset:9360
	ds_write_b16 v152, v185 offset:9504
	ds_write_b16_d16_hi v152, v185 offset:9648
	s_waitcnt lgkmcnt(0)
	s_barrier
	ds_read_b128 v[176:179], v173 offset:9216
	ds_read_b128 v[232:235], v107 offset:0
	ds_read_b128 v[184:187], v174 offset:9216
	ds_read_b128 v[180:183], v173 offset:9280
	ds_read_b128 v[236:239], v107 offset:64
	ds_read_b128 v[188:191], v174 offset:9280
	s_waitcnt lgkmcnt(4)
	v_mfma_f32_16x16x32_bf16 v[240:243], v[176:179], v[232:235], 0
	s_waitcnt lgkmcnt(3)
	v_mfma_f32_16x16x32_bf16 v[244:247], v[184:187], v[232:235], 0
	s_waitcnt lgkmcnt(1)
	v_mfma_f32_16x16x32_bf16 v[240:243], v[180:183], v[236:239], v[240:243]
	s_waitcnt lgkmcnt(0)
	v_mfma_f32_16x16x32_bf16 v[244:247], v[188:191], v[236:239], v[244:247]
	s_nop 7
	v_cvt_pk_bf16_f32 v176, v240, v241
	v_cvt_pk_bf16_f32 v177, v242, v243
	v_cvt_pk_bf16_f32 v184, v244, v245
	v_cvt_pk_bf16_f32 v185, v246, v247
	ds_write_b64 v97, v[102:103] offset:18432
	ds_write_b64 v97, v[176:177] offset:0
	ds_write_b16 v148, v176 offset:0
	ds_write_b16_d16_hi v148, v176 offset:144
	ds_write_b16 v148, v177 offset:288
	ds_write_b16_d16_hi v148, v177 offset:432
	ds_write_b64 v98, v[102:103] offset:18432
	ds_write_b64 v98, v[184:185] offset:0
	ds_write_b16 v149, v184 offset:0
	ds_write_b16_d16_hi v149, v184 offset:144
	ds_write_b16 v149, v185 offset:288
	ds_write_b16_d16_hi v149, v185 offset:432
	s_waitcnt lgkmcnt(0)
	s_barrier
	ds_read_b128 v[176:179], v175 offset:9216
	ds_read_b128 v[232:235], v132 offset:0
	ds_read_b128 v[184:187], v96 offset:9216
	ds_read_b128 v[180:183], v175 offset:9280
	ds_read_b128 v[236:239], v132 offset:64
	ds_read_b128 v[188:191], v96 offset:9280
	s_waitcnt lgkmcnt(4)
	v_mfma_f32_16x16x32_bf16 v[240:243], v[176:179], v[232:235], 0
	s_waitcnt lgkmcnt(3)
	v_mfma_f32_16x16x32_bf16 v[244:247], v[184:187], v[232:235], 0
	s_waitcnt lgkmcnt(1)
	v_mfma_f32_16x16x32_bf16 v[240:243], v[180:183], v[236:239], v[240:243]
	s_waitcnt lgkmcnt(0)
	v_mfma_f32_16x16x32_bf16 v[244:247], v[188:191], v[236:239], v[244:247]
	s_nop 7
	v_cvt_pk_bf16_f32 v176, v240, v241
	v_cvt_pk_bf16_f32 v177, v242, v243
	v_cvt_pk_bf16_f32 v184, v244, v245
	v_cvt_pk_bf16_f32 v185, v246, v247
	ds_write_b64 v127, v[102:103] offset:18432
	ds_write_b64 v127, v[176:177] offset:0
	ds_write_b16 v151, v176 offset:9216
	ds_write_b16_d16_hi v151, v176 offset:9360
	ds_write_b16 v151, v177 offset:9504
	ds_write_b16_d16_hi v151, v177 offset:9648
	ds_write_b64 v129, v[102:103] offset:18432
	ds_write_b64 v129, v[184:185] offset:0
	ds_write_b16 v152, v184 offset:9216
	ds_write_b16_d16_hi v152, v184 offset:9360
	ds_write_b16 v152, v185 offset:9504
	ds_write_b16_d16_hi v152, v185 offset:9648
	s_waitcnt lgkmcnt(0)
	s_barrier
	ds_read_b128 v[176:179], v173 offset:9216
	ds_read_b128 v[232:235], v107 offset:0
	ds_read_b128 v[184:187], v174 offset:9216
	ds_read_b128 v[180:183], v173 offset:9280
	ds_read_b128 v[236:239], v107 offset:64
	ds_read_b128 v[188:191], v174 offset:9280
	s_waitcnt lgkmcnt(4)
	v_mfma_f32_16x16x32_bf16 v[240:243], v[176:179], v[232:235], 0
	s_waitcnt lgkmcnt(3)
	v_mfma_f32_16x16x32_bf16 v[244:247], v[184:187], v[232:235], 0
	s_waitcnt lgkmcnt(1)
	v_mfma_f32_16x16x32_bf16 v[240:243], v[180:183], v[236:239], v[240:243]
	s_waitcnt lgkmcnt(0)
	v_mfma_f32_16x16x32_bf16 v[244:247], v[188:191], v[236:239], v[244:247]
	s_nop 7
	v_cvt_pk_bf16_f32 v176, v240, v241
	v_cvt_pk_bf16_f32 v177, v242, v243
	v_cvt_pk_bf16_f32 v184, v244, v245
	v_cvt_pk_bf16_f32 v185, v246, v247
	ds_write_b64 v97, v[102:103] offset:18432
	ds_write_b64 v97, v[176:177] offset:0
	ds_write_b16 v148, v176 offset:0
	ds_write_b16_d16_hi v148, v176 offset:144
	ds_write_b16 v148, v177 offset:288
	ds_write_b16_d16_hi v148, v177 offset:432
	ds_write_b64 v98, v[102:103] offset:18432
	ds_write_b64 v98, v[184:185] offset:0
	ds_write_b16 v149, v184 offset:0
	ds_write_b16_d16_hi v149, v184 offset:144
	ds_write_b16 v149, v185 offset:288
	ds_write_b16_d16_hi v149, v185 offset:432
	s_waitcnt lgkmcnt(0)
	s_barrier
	ds_read_b128 v[176:179], v175 offset:9216
	ds_read_b128 v[232:235], v132 offset:0
	ds_read_b128 v[184:187], v96 offset:9216
	ds_read_b128 v[180:183], v175 offset:9280
	ds_read_b128 v[236:239], v132 offset:64
	ds_read_b128 v[188:191], v96 offset:9280
	s_waitcnt lgkmcnt(4)
	v_mfma_f32_16x16x32_bf16 v[240:243], v[176:179], v[232:235], 0
	s_waitcnt lgkmcnt(3)
	v_mfma_f32_16x16x32_bf16 v[244:247], v[184:187], v[232:235], 0
	s_waitcnt lgkmcnt(1)
	v_mfma_f32_16x16x32_bf16 v[240:243], v[180:183], v[236:239], v[240:243]
	s_waitcnt lgkmcnt(0)
	v_mfma_f32_16x16x32_bf16 v[244:247], v[188:191], v[236:239], v[244:247]
	s_nop 7
	v_cvt_pk_bf16_f32 v176, v240, v241
	v_cvt_pk_bf16_f32 v177, v242, v243
	v_cvt_pk_bf16_f32 v184, v244, v245
	v_cvt_pk_bf16_f32 v185, v246, v247
	ds_write_b64 v127, v[102:103] offset:18432
	ds_write_b64 v127, v[176:177] offset:0
	ds_write_b16 v151, v176 offset:9216
	ds_write_b16_d16_hi v151, v176 offset:9360
	ds_write_b16 v151, v177 offset:9504
	ds_write_b16_d16_hi v151, v177 offset:9648
	ds_write_b64 v129, v[102:103] offset:18432
	ds_write_b64 v129, v[184:185] offset:0
	ds_write_b16 v152, v184 offset:9216
	ds_write_b16_d16_hi v152, v184 offset:9360
	ds_write_b16 v152, v185 offset:9504
	ds_write_b16_d16_hi v152, v185 offset:9648
	s_waitcnt lgkmcnt(0)
	s_barrier
	s_nop 7
	ds_write_b64 v97, v[102:103] offset:18432
	ds_write_b64 v98, v[102:103] offset:18432
	s_waitcnt lgkmcnt(0)
	s_barrier

; __global__ void __launch_bounds__(NWAVES * 64, 2) hybrid_fwd(const Args A) {
	.amdhsa_kernel _Z10hybrid_fwd4Args
		.amdhsa_group_segment_fixed_size 0
		.amdhsa_private_segment_fixed_size 0
		.amdhsa_kernarg_size 528
		.amdhsa_user_sgpr_count 2
		.amdhsa_user_sgpr_dispatch_ptr 0
		.amdhsa_user_sgpr_queue_ptr 0
		.amdhsa_user_sgpr_kernarg_segment_ptr 1
		.amdhsa_user_sgpr_dispatch_id 0
		.amdhsa_user_sgpr_kernarg_preload_length 0
		.amdhsa_user_sgpr_kernarg_preload_offset 0
		.amdhsa_user_sgpr_private_segment_size 0
		.amdhsa_uses_dynamic_stack 0
		.amdhsa_enable_private_segment 0
		.amdhsa_system_sgpr_workgroup_id_x 1
		.amdhsa_system_sgpr_workgroup_id_y 0
		.amdhsa_system_sgpr_workgroup_id_z 0
		.amdhsa_system_sgpr_workgroup_info 0
		.amdhsa_system_vgpr_workitem_id 2
		.amdhsa_next_free_vgpr 256
		.amdhsa_next_free_sgpr 102
		.amdhsa_accum_offset 256
		.amdhsa_reserve_vcc 1
		.amdhsa_float_round_mode_32 0
		.amdhsa_float_round_mode_16_64 0
		.amdhsa_float_denorm_mode_32 3
		.amdhsa_float_denorm_mode_16_64 3
		.amdhsa_dx10_clamp 1
		.amdhsa_ieee_mode 1
		.amdhsa_fp16_overflow 0
		.amdhsa_tg_split 0
		.amdhsa_exception_fp_ieee_invalid_op 0
		.amdhsa_exception_fp_denorm_src 0
		.amdhsa_exception_fp_ieee_div_zero 0
		.amdhsa_exception_fp_ieee_overflow 0
		.amdhsa_exception_fp_ieee_underflow 0
		.amdhsa_exception_fp_ieee_inexact 0
		.amdhsa_exception_int_div_zero 0
	.end_amdhsa_kernel

; __global__ void __launch_bounds__(NWAVES * 64, 2) hybrid_fwd(const Args A) {
amdhsa.kernels:
  - .agpr_count:     0
    .args:
      - .offset:         0
        .size:           272
        .value_kind:     by_value
      - .offset:         272
        .size:           4
        .value_kind:     hidden_block_count_x
      - .offset:         276
        .size:           4
        .value_kind:     hidden_block_count_y
      - .offset:         280
        .size:           4
        .value_kind:     hidden_block_count_z
      - .offset:         284
        .size:           2
        .value_kind:     hidden_group_size_x
      - .offset:         286
        .size:           2
        .value_kind:     hidden_group_size_y
      - .offset:         288
        .size:           2
        .value_kind:     hidden_group_size_z
      - .offset:         290
        .size:           2
        .value_kind:     hidden_remainder_x
      - .offset:         292
        .size:           2
        .value_kind:     hidden_remainder_y
      - .offset:         294
        .size:           2
        .value_kind:     hidden_remainder_z
      - .offset:         312
        .size:           8
        .value_kind:     hidden_global_offset_x
      - .offset:         320
        .size:           8
        .value_kind:     hidden_global_offset_y
      - .offset:         328
        .size:           8
        .value_kind:     hidden_global_offset_z
      - .offset:         336
        .size:           2
        .value_kind:     hidden_grid_dims
      - .offset:         360
        .size:           8
        .value_kind:     hidden_multigrid_sync_arg
      - .offset:         392
        .size:           4
        .value_kind:     hidden_dynamic_lds_size
    .group_segment_fixed_size: 0
    .kernarg_segment_align: 8
    .kernarg_segment_size: 528
    .language:       OpenCL C
    .language_version:
      - 2
      - 0
    .max_flat_workgroup_size: 512
    .name:           _Z10hybrid_fwd4Args
    .private_segment_fixed_size: 0
    .sgpr_count:     108
    .sgpr_spill_count: 85
    .symbol:         _Z10hybrid_fwd4Args.kd
    .uniform_work_group_size: 1
    .uses_dynamic_stack: false
    .vgpr_count:     256
    .vgpr_spill_count: 0
    .wavefront_size: 64
